# stick-breaking quarters: all K and V fragment reads issued up front, one LDS round trip before the Q.K MFMAs
# baseline (speedup 1.0000x reference)
; #define LAS __attribute__((address_space(3)))
; #define S_LOAD(key0) do { st0 = *(const u32x4*)(kg + (size_t)(key0) * 1024); st1 = *(const u32x4*)(kg + (size_t)((key0) + 64) * 1024); st2 = *(const u32x4*)(vg + (size_t)(key0) * 1024); st3 = *(const u32x4*)(vg + (size_t)((key0) + 64) * 1024); } while (0)
; __device__ __forceinline__ void sb_unit(const Frame& F, int b, int hd, int qi, int dry) {
;     ...
;     for (int it = 0; it < nt; ++it) {
;         const bool meta = (it > jmax);
;         const int key0 = meta ? 0 : NMETA + 128 * (jmax - it);
;         if (it + 1 < nt) { const int nk = (it + 1 > jmax) ? 0 : NMETA + 128 * (jmax - it - 1); S_LOAD(nk); }
;         if (!dead && (meta || key0 < tqw + 31)) {
;             const LAS unsigned char* kb = lds + kra + (it & 1) * SK_BUF;
;             const LAS unsigned char* vb = lds + vra + (it & 1) * SV_BUF;
;     ...
;             float run = C;
;             if (!meta && key0 + 96 < tqw + 31) SB_HALF(96);
.LBB0_337:
	s_xor_b64 s[0:1], s[0:1], -1
	s_andn2_b64 vcc, exec, s[0:1]
	s_mov_b64 s[0:1], -1
	s_cbranch_vccnz .LBB0_350
	s_add_i32 s35, s33, 0xffffff10
	s_cmp_gt_u32 s36, s29
	s_cselect_b64 s[18:19], -1, 0
	s_and_b64 s[0:1], s[18:19], exec
	s_cselect_b32 s35, 0, s35
	s_cmp_lt_i32 s35, s30
	s_cselect_b64 s[0:1], -1, 0
	s_or_b64 s[0:1], s[18:19], s[0:1]
	s_andn2_b64 vcc, exec, s[0:1]
	s_mov_b64 s[0:1], 0
	s_cbranch_vccnz .LBB0_350
	s_and_b32 s0, s36, 1
	s_mul_i32 s36, s0, 0x4800
	s_mul_i32 s37, s0, 0x6000
	s_or_b32 s0, s35, 0x41
	s_cmp_ge_i32 s0, s26
	s_cselect_b64 s[0:1], -1, 0
	s_or_b64 s[0:1], s[18:19], s[0:1]
	s_and_b64 vcc, exec, s[0:1]
	v_add_u32_e32 v129, s36, v118
	v_or_b32_e32 v127, s35, v205
	v_add_u32_e32 v128, s37, v119
	s_cbranch_vccnz .LBB0_341
	ds_read_b128 v[32:35], v129 offset:13824
	ds_read_b128 v[214:217], v129 offset:13856
	ds_read_b128 v[210:213], v129 offset:13888
	ds_read_b128 v[130:133], v129 offset:13920
	ds_read_b64_tr_b16 v[92:93], v128 offset:55296
	ds_read_b64_tr_b16 v[94:95], v128 offset:56832
	ds_read_b64_tr_b16 v[90:91], v128 offset:56896
	ds_read_b64_tr_b16 v[88:89], v128 offset:55360
	ds_read_b64_tr_b16 v[84:85], v128 offset:58368
	ds_read_b64_tr_b16 v[86:87], v128 offset:59904
	ds_read_b64_tr_b16 v[82:83], v128 offset:59968
	ds_read_b64_tr_b16 v[80:81], v128 offset:58432
	v_exp_f32_e32 v135, v125
	v_sub_u32_e32 v134, v115, v127
	v_cmp_lt_i32_e32 vcc, 0, v134
	s_waitcnt lgkmcnt(11)
	v_mfma_f32_32x32x16_bf16 v[32:47], v[32:35], v[48:51], 0
	v_cmp_lt_i32_e64 s[0:1], 27, v134
	s_waitcnt lgkmcnt(10)
	v_mfma_f32_32x32x16_bf16 v[32:47], v[214:217], v[52:55], v[32:47]
	s_waitcnt lgkmcnt(9)
	v_mfma_f32_32x32x16_bf16 v[32:47], v[210:213], v[56:59], v[32:47]
	s_waitcnt lgkmcnt(8)
	v_mfma_f32_32x32x16_bf16 v[32:47], v[130:133], v[60:63], v[32:47]
	s_nop 11
	v_min_f32_e64 v32, -v32, s60
	v_min_f32_e64 v33, -v33, s60
	v_exp_f32_e32 v32, v32
	v_min_f32_e64 v34, -v34, s60
	v_exp_f32_e32 v33, v33
	v_exp_f32_e32 v34, v34
	v_min_f32_e64 v35, -v35, s60
	v_exp_f32_e32 v130, v35
	v_add_f32_e32 v35, 1.0, v32
	v_add_f32_e32 v131, 1.0, v33
	v_rcp_f32_e32 v35, v35
	v_add_f32_e32 v132, 1.0, v34
	v_rcp_f32_e32 v131, v131
	v_min_f32_e64 v36, -v36, s60
	v_rcp_f32_e32 v132, v132
	v_exp_f32_e32 v36, v36
	v_add_f32_e32 v133, 1.0, v130
	v_rcp_f32_e32 v136, v133
	v_mul_f32_e32 v32, v32, v35
	v_mul_f32_e32 v133, v135, v35
	v_mul_f32_e32 v33, v33, v131
	v_mul_f32_e32 v137, v135, v131
	v_cndmask_b32_e32 v35, 1.0, v32, vcc
	v_cndmask_b32_e32 v138, 0, v133, vcc
	v_cmp_lt_i32_e32 vcc, 1, v134
	v_mul_f32_e32 v34, v34, v132
	v_mul_f32_e32 v32, v135, v132
	v_cndmask_b32_e32 v131, 1.0, v33, vcc
	v_cndmask_b32_e32 v137, 0, v137, vcc
	v_cmp_lt_i32_e32 vcc, 2, v134
	v_min_f32_e64 v39, -v39, s60
	v_cndmask_b32_e32 v33, 1.0, v34, vcc
	v_add_f32_e32 v34, 1.0, v36
	v_rcp_f32_e32 v34, v34
	v_cndmask_b32_e32 v139, 0, v32, vcc
	v_mul_f32_e32 v32, v130, v136
	v_cmp_lt_i32_e32 vcc, 3, v134
	v_exp_f32_e32 v39, v39
	v_cndmask_b32_e32 v133, 1.0, v32, vcc
	v_mul_f32_e32 v32, v135, v136
	v_cndmask_b32_e32 v136, 0, v32, vcc
	v_mul_f32_e32 v32, v36, v34
	v_min_f32_e64 v36, -v37, s60
	v_exp_f32_e32 v36, v36
	v_cmp_lt_i32_e32 vcc, 8, v134
	v_mul_f32_e32 v34, v135, v34
	v_cndmask_b32_e32 v140, 0, v34, vcc
	v_add_f32_e32 v34, 1.0, v36
	v_rcp_f32_e32 v34, v34
	v_min_f32_e64 v37, -v38, s60
	v_exp_f32_e32 v37, v37
	v_cndmask_b32_e32 v32, 1.0, v32, vcc
	v_mul_f32_e32 v36, v36, v34
	v_cmp_lt_i32_e32 vcc, 9, v134
	v_mul_f32_e32 v34, v135, v34
	v_min_f32_e64 v42, -v42, s60
	v_cndmask_b32_e32 v38, 1.0, v36, vcc
	v_add_f32_e32 v36, 1.0, v37
	v_rcp_f32_e32 v36, v36
	v_cndmask_b32_e32 v141, 0, v34, vcc
	v_cmp_lt_i32_e32 vcc, 10, v134
	v_exp_f32_e32 v42, v42
	v_mul_f32_e32 v34, v37, v36
	v_add_f32_e32 v37, 1.0, v39
	v_rcp_f32_e32 v37, v37
	v_cndmask_b32_e32 v142, 1.0, v34, vcc
	v_mul_f32_e32 v34, v135, v36
	v_cndmask_b32_e32 v143, 0, v34, vcc
	v_mul_f32_e32 v34, v39, v37
	v_cmp_lt_i32_e32 vcc, 11, v134
	v_min_f32_e64 v36, -v40, s60
	v_exp_f32_e32 v36, v36
	v_cndmask_b32_e32 v39, 1.0, v34, vcc
	v_mul_f32_e32 v34, v135, v37
	v_min_f32_e64 v37, -v41, s60
	v_exp_f32_e32 v37, v37
	v_cndmask_b32_e32 v40, 0, v34, vcc
	v_add_f32_e32 v34, 1.0, v36
	v_rcp_f32_e32 v34, v34
	v_add_f32_e32 v41, 1.0, v37
	v_rcp_f32_e32 v41, v41
	v_cmp_lt_i32_e32 vcc, 16, v134
	v_mul_f32_e32 v36, v36, v34
	v_mul_f32_e32 v34, v135, v34
	v_cndmask_b32_e32 v144, 0, v34, vcc
	v_mul_f32_e32 v34, v37, v41
	v_add_f32_e32 v37, 1.0, v42
	v_rcp_f32_e32 v37, v37
	v_cndmask_b32_e32 v36, 1.0, v36, vcc
	v_cmp_lt_i32_e32 vcc, 17, v134
	v_min_f32_e64 v45, -v45, s60
	v_cndmask_b32_e32 v145, 1.0, v34, vcc
	v_mul_f32_e32 v34, v135, v41
	v_cndmask_b32_e32 v41, 0, v34, vcc
	v_mul_f32_e32 v34, v42, v37
	v_cmp_lt_i32_e32 vcc, 18, v134
	v_min_f32_e64 v42, -v43, s60
	v_exp_f32_e32 v42, v42
	v_cndmask_b32_e32 v43, 1.0, v34, vcc
	v_mul_f32_e32 v34, v135, v37
	v_min_f32_e64 v37, -v44, s60
	v_exp_f32_e32 v37, v37
	v_cndmask_b32_e32 v146, 0, v34, vcc
	v_add_f32_e32 v34, 1.0, v42
	v_rcp_f32_e32 v34, v34
	v_add_f32_e32 v44, 1.0, v37
	v_rcp_f32_e32 v44, v44
	v_exp_f32_e32 v45, v45
	v_min_f32_e64 v46, -v46, s60
	v_min_f32_e64 v47, -v47, s60
	v_exp_f32_e32 v46, v46
	v_exp_f32_e32 v47, v47
	v_mul_f32_e32 v42, v42, v34
	v_cmp_lt_i32_e32 vcc, 19, v134
	v_mul_f32_e32 v34, v135, v34
	v_add_f32_e32 v130, 1.0, v46
	v_cndmask_b32_e32 v147, 0, v34, vcc
	v_mul_f32_e32 v34, v37, v44
	v_add_f32_e32 v37, 1.0, v45
	v_rcp_f32_e32 v37, v37
	v_add_f32_e32 v132, 1.0, v47
	v_rcp_f32_e32 v130, v130
	v_rcp_f32_e32 v132, v132
	v_cndmask_b32_e32 v42, 1.0, v42, vcc
	v_cmp_lt_i32_e32 vcc, 24, v134
	v_mul_f32_e32 v44, v135, v44
	v_mul_f32_e32 v45, v45, v37
	v_cndmask_b32_e32 v34, 1.0, v34, vcc
	v_cndmask_b32_e32 v44, 0, v44, vcc
	v_cmp_lt_i32_e32 vcc, 25, v134
	v_mul_f32_e32 v37, v135, v37
	v_mul_f32_e32 v46, v46, v130
	v_cndmask_b32_e32 v45, 1.0, v45, vcc
	v_cndmask_b32_e32 v37, 0, v37, vcc
	v_cmp_lt_i32_e32 vcc, 26, v134
	v_mul_f32_e32 v47, v47, v132
	v_cndmask_b32_e64 v47, 1.0, v47, s[0:1]
	v_cndmask_b32_e32 v46, 1.0, v46, vcc
	v_mul_f32_e32 v34, v34, v45
	v_mul_f32_e32 v134, v46, v47
	v_mul_f32_e32 v134, v34, v134
	v_mov_b32_e32 v148, v134
	v_mov_b32_e32 v240, v134
	s_nop 1
	v_permlane32_swap_b32_e32 v148, v240
	v_cndmask_b32_e64 v148, v148, v240, s[2:3]
	v_mul_f32_e32 v34, v135, v130
	v_cndmask_b32_e32 v149, 0, v34, vcc
	v_mul_f32_e32 v34, v135, v132
	v_cndmask_b32_e64 v34, 0, v34, s[0:1]
	s_waitcnt lgkmcnt(0)
; __device__ __forceinline__ void sb_unit(const Frame& F, int b, int hd, int qi, int dry) {
;     ...
;             float run = C;
;             if (!meta && key0 + 96 < tqw + 31) SB_HALF(96);
;             if (!meta && key0 + 64 < tqw + 31 && __any(run >= SB_DEAD)) SB_HALF(64);
	v_cndmask_b32_e64 v130, 1.0, v148, s[2:3]
	v_mul_f32_e32 v135, v34, v130
	v_mul_f32_e32 v34, v36, v145
	v_mul_f32_e32 v36, v43, v42
	v_mul_f32_e32 v36, v34, v36
	v_mul_f32_e32 v32, v32, v38
	v_mul_f32_e32 v34, v142, v39
	v_mov_b32_e32 v150, v36
	v_mov_b32_e32 v240, v36
	s_nop 1
	v_permlane32_swap_b32_e32 v150, v240
	v_cndmask_b32_e64 v150, v150, v240, s[2:3]
	v_mul_f32_e32 v34, v32, v34
	v_mul_f32_e32 v47, v47, v130
	v_mov_b32_e32 v130, v34
	v_mov_b32_e32 v240, v34
	s_nop 1
	v_permlane32_swap_b32_e32 v130, v240
	v_cndmask_b32_e64 v130, v130, v240, s[2:3]
	v_mul_f32_e32 v46, v46, v47
	v_mul_f32_e32 v32, v134, v148
	s_waitcnt lgkmcnt(1)
	v_mul_f32_e32 v132, v36, v150
	v_mul_f32_e32 v45, v45, v46
	v_mul_f32_e32 v46, v37, v46
	s_waitcnt lgkmcnt(0)
	v_cndmask_b32_e64 v134, 1.0, v130, s[2:3]
	v_pk_mul_f32 v[36:37], v[32:33], v[132:133]
	v_pk_mul_f32 v[34:35], v[34:35], v[130:131]
	v_mul_f32_e32 v132, v36, v134
	v_mul_f32_e32 v134, v39, v132
	v_mul_f32_e32 v142, v142, v134
	v_mul_f32_e32 v148, v38, v142
	v_pk_mul_f32 v[38:39], v[34:35], v[36:37]
	v_mov_b32_e32 v130, v39
	v_mov_b32_e32 v240, v39
	s_nop 1
	v_permlane32_swap_b32_e32 v130, v240
	v_cndmask_b32_e64 v130, v130, v240, s[2:3]
	v_mul_f32_e32 v37, v40, v132
	v_mul_f32_e32 v40, v143, v134
	v_mul_f32_e32 v36, v141, v142
	v_mul_f32_e32 v132, v140, v148
	s_waitcnt lgkmcnt(0)
	v_cndmask_b32_e64 v34, 1.0, v130, s[2:3]
	v_mul_f32_e32 v34, v38, v34
	v_mul_f32_e32 v35, v133, v34
	v_mul_f32_e32 v33, v33, v35
	v_mul_f32_e32 v131, v131, v33
	v_mul_f32_e32 v133, v136, v34
	v_mul_f32_e32 v35, v139, v35
	v_mul_f32_e32 v33, v137, v33
	v_mul_f32_e32 v34, v138, v131
	v_cvt_pk_bf16_f32 v34, v34, v33
	v_cvt_pk_bf16_f32 v35, v35, v133
	v_cvt_pk_bf16_f32 v36, v132, v36
	v_cvt_pk_bf16_f32 v37, v40, v37
	v_cndmask_b32_e64 v33, 1.0, v150, s[2:3]
	v_mul_f32_e32 v32, v32, v33
	v_mfma_f32_32x32x16_bf16 v[16:31], v[92:95], v[34:37], v[16:31]
	v_mul_f32_e32 v33, v42, v32
	v_mul_f32_e32 v42, v43, v33
	v_mul_f32_e32 v43, v145, v42
	v_mul_f32_e32 v47, v149, v47
	v_mul_f32_e32 v40, v44, v45
	v_mul_f32_e32 v44, v147, v32
	v_mul_f32_e32 v33, v146, v33
	v_mfma_f32_32x32x16_bf16 v[0:15], v[88:91], v[34:37], v[0:15]
	v_mul_f32_e32 v32, v41, v42
	v_mul_f32_e32 v34, v144, v43
	v_cvt_pk_bf16_f32 v32, v34, v32
	v_cvt_pk_bf16_f32 v33, v33, v44
	v_cvt_pk_bf16_f32 v34, v40, v46
	v_cvt_pk_bf16_f32 v35, v47, v135
	v_mul_f32_e32 v36, v39, v130
	v_mul_f32_e32 v36, v38, v36
	v_mfma_f32_32x32x16_bf16 v[16:31], v[84:87], v[32:35], v[16:31]
	v_log_f32_e32 v36, v36
	s_nop 0
	v_add_f32_e32 v125, v125, v36
	v_mfma_f32_32x32x16_bf16 v[0:15], v[80:83], v[32:35], v[0:15]
.LBB0_341:
	s_or_b32 s0, s35, 33
	s_cmp_ge_i32 s0, s26
	s_cselect_b64 s[0:1], -1, 0
	s_or_b64 s[0:1], s[18:19], s[0:1]
	s_and_b64 vcc, exec, s[0:1]
	s_cbranch_vccnz .LBB0_344
	v_cmp_le_f32_e32 vcc, s22, v125
	s_cbranch_vccz .LBB0_344
	ds_read_b128 v[32:35], v129 offset:9216
	ds_read_b128 v[214:217], v129 offset:9248
	ds_read_b128 v[210:213], v129 offset:9280
	ds_read_b128 v[130:133], v129 offset:9312
	ds_read_b64_tr_b16 v[92:93], v128 offset:49152
	ds_read_b64_tr_b16 v[94:95], v128 offset:50688
	ds_read_b64_tr_b16 v[90:91], v128 offset:50752
	ds_read_b64_tr_b16 v[88:89], v128 offset:49216
	ds_read_b64_tr_b16 v[84:85], v128 offset:52224
	ds_read_b64_tr_b16 v[86:87], v128 offset:53760
	ds_read_b64_tr_b16 v[82:83], v128 offset:53824
	ds_read_b64_tr_b16 v[80:81], v128 offset:52288
	v_exp_f32_e32 v135, v125
	v_sub_u32_e32 v134, v124, v127
	v_cmp_lt_i32_e32 vcc, 0, v134
	s_waitcnt lgkmcnt(11)
	v_mfma_f32_32x32x16_bf16 v[32:47], v[32:35], v[48:51], 0
	v_cmp_lt_i32_e64 s[0:1], 27, v134
	s_waitcnt lgkmcnt(10)
	v_mfma_f32_32x32x16_bf16 v[32:47], v[214:217], v[52:55], v[32:47]
	s_waitcnt lgkmcnt(9)
	v_mfma_f32_32x32x16_bf16 v[32:47], v[210:213], v[56:59], v[32:47]
	s_waitcnt lgkmcnt(8)
	v_mfma_f32_32x32x16_bf16 v[32:47], v[130:133], v[60:63], v[32:47]
	s_nop 11
	v_min_f32_e64 v32, -v32, s60
	v_min_f32_e64 v33, -v33, s60
	v_exp_f32_e32 v32, v32
	v_min_f32_e64 v34, -v34, s60
	v_exp_f32_e32 v33, v33
	v_exp_f32_e32 v34, v34
	v_min_f32_e64 v35, -v35, s60
	v_exp_f32_e32 v130, v35
	v_add_f32_e32 v35, 1.0, v32
	v_add_f32_e32 v131, 1.0, v33
	v_rcp_f32_e32 v35, v35
	v_add_f32_e32 v132, 1.0, v34
	v_rcp_f32_e32 v131, v131
	v_min_f32_e64 v36, -v36, s60
	v_rcp_f32_e32 v132, v132
	v_exp_f32_e32 v36, v36
	v_add_f32_e32 v133, 1.0, v130
	v_rcp_f32_e32 v136, v133
	v_mul_f32_e32 v32, v32, v35
	v_mul_f32_e32 v133, v135, v35
	v_mul_f32_e32 v33, v33, v131
	v_mul_f32_e32 v137, v135, v131
	v_cndmask_b32_e32 v35, 1.0, v32, vcc
	v_cndmask_b32_e32 v138, 0, v133, vcc
	v_cmp_lt_i32_e32 vcc, 1, v134
	v_mul_f32_e32 v34, v34, v132
	v_mul_f32_e32 v32, v135, v132
	v_cndmask_b32_e32 v131, 1.0, v33, vcc
	v_cndmask_b32_e32 v137, 0, v137, vcc
	v_cmp_lt_i32_e32 vcc, 2, v134
	v_min_f32_e64 v39, -v39, s60
	v_cndmask_b32_e32 v33, 1.0, v34, vcc
	v_add_f32_e32 v34, 1.0, v36
	v_rcp_f32_e32 v34, v34
	v_cndmask_b32_e32 v139, 0, v32, vcc
	v_mul_f32_e32 v32, v130, v136
	v_cmp_lt_i32_e32 vcc, 3, v134
	v_exp_f32_e32 v39, v39
	v_cndmask_b32_e32 v133, 1.0, v32, vcc
	v_mul_f32_e32 v32, v135, v136
	v_cndmask_b32_e32 v136, 0, v32, vcc
	v_mul_f32_e32 v32, v36, v34
	v_min_f32_e64 v36, -v37, s60
	v_exp_f32_e32 v36, v36
	v_cmp_lt_i32_e32 vcc, 8, v134
	v_mul_f32_e32 v34, v135, v34
	v_cndmask_b32_e32 v140, 0, v34, vcc
	v_add_f32_e32 v34, 1.0, v36
	v_rcp_f32_e32 v34, v34
	v_min_f32_e64 v37, -v38, s60
	v_exp_f32_e32 v37, v37
	v_cndmask_b32_e32 v32, 1.0, v32, vcc
	v_mul_f32_e32 v36, v36, v34
	v_cmp_lt_i32_e32 vcc, 9, v134
	v_mul_f32_e32 v34, v135, v34
	v_min_f32_e64 v42, -v42, s60
	v_cndmask_b32_e32 v38, 1.0, v36, vcc
	v_add_f32_e32 v36, 1.0, v37
	v_rcp_f32_e32 v36, v36
	v_cndmask_b32_e32 v141, 0, v34, vcc
	v_cmp_lt_i32_e32 vcc, 10, v134
	v_exp_f32_e32 v42, v42
	v_mul_f32_e32 v34, v37, v36
	v_add_f32_e32 v37, 1.0, v39
	v_rcp_f32_e32 v37, v37
	v_cndmask_b32_e32 v142, 1.0, v34, vcc
	v_mul_f32_e32 v34, v135, v36
	v_cndmask_b32_e32 v143, 0, v34, vcc
	v_mul_f32_e32 v34, v39, v37
	v_cmp_lt_i32_e32 vcc, 11, v134
	v_min_f32_e64 v36, -v40, s60
	v_exp_f32_e32 v36, v36
	v_cndmask_b32_e32 v39, 1.0, v34, vcc
	v_mul_f32_e32 v34, v135, v37
	v_min_f32_e64 v37, -v41, s60
	v_exp_f32_e32 v37, v37
	v_cndmask_b32_e32 v40, 0, v34, vcc
	v_add_f32_e32 v34, 1.0, v36
	v_rcp_f32_e32 v34, v34
	v_add_f32_e32 v41, 1.0, v37
	v_rcp_f32_e32 v41, v41
	v_cmp_lt_i32_e32 vcc, 16, v134
	v_mul_f32_e32 v36, v36, v34
	v_mul_f32_e32 v34, v135, v34
	v_cndmask_b32_e32 v144, 0, v34, vcc
	v_mul_f32_e32 v34, v37, v41
	v_add_f32_e32 v37, 1.0, v42
	v_rcp_f32_e32 v37, v37
	v_cndmask_b32_e32 v36, 1.0, v36, vcc
	v_cmp_lt_i32_e32 vcc, 17, v134
	v_min_f32_e64 v45, -v45, s60
	v_cndmask_b32_e32 v145, 1.0, v34, vcc
	v_mul_f32_e32 v34, v135, v41
	v_cndmask_b32_e32 v41, 0, v34, vcc
	v_mul_f32_e32 v34, v42, v37
	v_cmp_lt_i32_e32 vcc, 18, v134
	v_min_f32_e64 v42, -v43, s60
	v_exp_f32_e32 v42, v42
	v_cndmask_b32_e32 v43, 1.0, v34, vcc
	v_mul_f32_e32 v34, v135, v37
	v_min_f32_e64 v37, -v44, s60
	v_exp_f32_e32 v37, v37
	v_cndmask_b32_e32 v146, 0, v34, vcc
	v_add_f32_e32 v34, 1.0, v42
	v_rcp_f32_e32 v34, v34
	v_add_f32_e32 v44, 1.0, v37
	v_rcp_f32_e32 v44, v44
	v_exp_f32_e32 v45, v45
	v_min_f32_e64 v46, -v46, s60
	v_min_f32_e64 v47, -v47, s60
	v_exp_f32_e32 v46, v46
	v_exp_f32_e32 v47, v47
	v_mul_f32_e32 v42, v42, v34
	v_cmp_lt_i32_e32 vcc, 19, v134
	v_mul_f32_e32 v34, v135, v34
	v_add_f32_e32 v130, 1.0, v46
	v_cndmask_b32_e32 v147, 0, v34, vcc
	v_mul_f32_e32 v34, v37, v44
	v_add_f32_e32 v37, 1.0, v45
	v_rcp_f32_e32 v37, v37
	v_add_f32_e32 v132, 1.0, v47
	v_rcp_f32_e32 v130, v130
	v_rcp_f32_e32 v132, v132
	v_cndmask_b32_e32 v42, 1.0, v42, vcc
	v_cmp_lt_i32_e32 vcc, 24, v134
	v_mul_f32_e32 v44, v135, v44
	v_mul_f32_e32 v45, v45, v37
	v_cndmask_b32_e32 v34, 1.0, v34, vcc
	v_cndmask_b32_e32 v44, 0, v44, vcc
	v_cmp_lt_i32_e32 vcc, 25, v134
	v_mul_f32_e32 v37, v135, v37
	v_mul_f32_e32 v46, v46, v130
	v_cndmask_b32_e32 v45, 1.0, v45, vcc
	v_cndmask_b32_e32 v37, 0, v37, vcc
	v_cmp_lt_i32_e32 vcc, 26, v134
	v_mul_f32_e32 v47, v47, v132
	v_cndmask_b32_e64 v47, 1.0, v47, s[0:1]
	v_cndmask_b32_e32 v46, 1.0, v46, vcc
	v_mul_f32_e32 v34, v34, v45
	v_mul_f32_e32 v134, v46, v47
	v_mul_f32_e32 v134, v34, v134
	v_mov_b32_e32 v148, v134
	v_mov_b32_e32 v240, v134
	s_nop 1
	v_permlane32_swap_b32_e32 v148, v240
	v_cndmask_b32_e64 v148, v148, v240, s[2:3]
	v_mul_f32_e32 v34, v135, v130
	v_cndmask_b32_e32 v149, 0, v34, vcc
	v_mul_f32_e32 v34, v135, v132
	v_cndmask_b32_e64 v34, 0, v34, s[0:1]
	s_waitcnt lgkmcnt(0)
	v_cndmask_b32_e64 v130, 1.0, v148, s[2:3]
	v_mul_f32_e32 v135, v34, v130
	v_mul_f32_e32 v34, v36, v145
	v_mul_f32_e32 v36, v43, v42
	v_mul_f32_e32 v36, v34, v36
	v_mul_f32_e32 v32, v32, v38
	v_mul_f32_e32 v34, v142, v39
	v_mov_b32_e32 v150, v36
	v_mov_b32_e32 v240, v36
	s_nop 1
	v_permlane32_swap_b32_e32 v150, v240
	v_cndmask_b32_e64 v150, v150, v240, s[2:3]
	v_mul_f32_e32 v34, v32, v34
	v_mul_f32_e32 v47, v47, v130
	v_mov_b32_e32 v130, v34
	v_mov_b32_e32 v240, v34
	s_nop 1
	v_permlane32_swap_b32_e32 v130, v240
	v_cndmask_b32_e64 v130, v130, v240, s[2:3]
	v_mul_f32_e32 v46, v46, v47
	v_mul_f32_e32 v32, v134, v148
	s_waitcnt lgkmcnt(1)
	v_mul_f32_e32 v132, v36, v150
	v_mul_f32_e32 v45, v45, v46
	v_mul_f32_e32 v46, v37, v46
	s_waitcnt lgkmcnt(0)
	v_cndmask_b32_e64 v134, 1.0, v130, s[2:3]
	v_pk_mul_f32 v[36:37], v[32:33], v[132:133]
	v_pk_mul_f32 v[34:35], v[34:35], v[130:131]
	v_mul_f32_e32 v132, v36, v134
	v_mul_f32_e32 v134, v39, v132
	v_mul_f32_e32 v142, v142, v134
	v_mul_f32_e32 v148, v38, v142
	v_pk_mul_f32 v[38:39], v[34:35], v[36:37]
	v_mov_b32_e32 v130, v39
	v_mov_b32_e32 v240, v39
	s_nop 1
	v_permlane32_swap_b32_e32 v130, v240
	v_cndmask_b32_e64 v130, v130, v240, s[2:3]
	v_mul_f32_e32 v37, v40, v132
	v_mul_f32_e32 v40, v143, v134
	v_mul_f32_e32 v36, v141, v142
	v_mul_f32_e32 v132, v140, v148
	s_waitcnt lgkmcnt(0)
	v_cndmask_b32_e64 v34, 1.0, v130, s[2:3]
	v_mul_f32_e32 v34, v38, v34
	v_mul_f32_e32 v35, v133, v34
	v_mul_f32_e32 v33, v33, v35
	v_mul_f32_e32 v131, v131, v33
	v_mul_f32_e32 v133, v136, v34
	v_mul_f32_e32 v35, v139, v35
	v_mul_f32_e32 v33, v137, v33
	v_mul_f32_e32 v34, v138, v131
	v_cvt_pk_bf16_f32 v34, v34, v33
	v_cvt_pk_bf16_f32 v35, v35, v133
	v_cvt_pk_bf16_f32 v36, v132, v36
	v_cvt_pk_bf16_f32 v37, v40, v37
	v_cndmask_b32_e64 v33, 1.0, v150, s[2:3]
	v_mul_f32_e32 v32, v32, v33
	v_mfma_f32_32x32x16_bf16 v[16:31], v[92:95], v[34:37], v[16:31]
	v_mul_f32_e32 v33, v42, v32
	v_mul_f32_e32 v42, v43, v33
	v_mul_f32_e32 v43, v145, v42
	v_mul_f32_e32 v47, v149, v47
	v_mul_f32_e32 v40, v44, v45
	v_mul_f32_e32 v44, v147, v32
	v_mul_f32_e32 v33, v146, v33
	v_mfma_f32_32x32x16_bf16 v[0:15], v[88:91], v[34:37], v[0:15]
	v_mul_f32_e32 v32, v41, v42
	v_mul_f32_e32 v34, v144, v43
	v_cvt_pk_bf16_f32 v32, v34, v32
	v_cvt_pk_bf16_f32 v33, v33, v44
	v_cvt_pk_bf16_f32 v34, v40, v46
	v_cvt_pk_bf16_f32 v35, v47, v135
	v_mul_f32_e32 v36, v39, v130
	v_mul_f32_e32 v36, v38, v36
	v_mfma_f32_32x32x16_bf16 v[16:31], v[84:87], v[32:35], v[16:31]
	v_log_f32_e32 v36, v36
	s_nop 0
	v_add_f32_e32 v125, v125, v36
	v_mfma_f32_32x32x16_bf16 v[0:15], v[80:83], v[32:35], v[0:15]
; __device__ __forceinline__ void sb_unit(const Frame& F, int b, int hd, int qi, int dry) {
;     ...
;             float run = C;
;             if (!meta && key0 + 96 < tqw + 31) SB_HALF(96);
;             if (!meta && key0 + 64 < tqw + 31 && __any(run >= SB_DEAD)) SB_HALF(64);
;             if (!meta && key0 + 32 < tqw + 31 && __any(run >= SB_DEAD)) SB_HALF(32);
.LBB0_344:
	s_or_b32 s0, s35, 1
	s_cmp_ge_i32 s0, s26
	s_cselect_b64 s[0:1], -1, 0
	s_or_b64 s[0:1], s[18:19], s[0:1]
	s_and_b64 vcc, exec, s[0:1]
	s_cbranch_vccnz .LBB0_347
	v_cmp_le_f32_e32 vcc, s22, v125
	s_cbranch_vccz .LBB0_347
	ds_read_b128 v[32:35], v129 offset:4608
	ds_read_b128 v[214:217], v129 offset:4640
	ds_read_b128 v[210:213], v129 offset:4672
	ds_read_b128 v[130:133], v129 offset:4704
	ds_read_b64_tr_b16 v[92:93], v128 offset:43008
	ds_read_b64_tr_b16 v[94:95], v128 offset:44544
	ds_read_b64_tr_b16 v[90:91], v128 offset:44608
	ds_read_b64_tr_b16 v[88:89], v128 offset:43072
	ds_read_b64_tr_b16 v[84:85], v128 offset:46080
	ds_read_b64_tr_b16 v[86:87], v128 offset:47616
	ds_read_b64_tr_b16 v[82:83], v128 offset:47680
	ds_read_b64_tr_b16 v[80:81], v128 offset:46144
	v_exp_f32_e32 v135, v125
	v_sub_u32_e32 v134, v126, v127
	v_cmp_lt_i32_e32 vcc, 0, v134
	s_waitcnt lgkmcnt(11)
	v_mfma_f32_32x32x16_bf16 v[32:47], v[32:35], v[48:51], 0
	v_cmp_lt_i32_e64 s[0:1], 27, v134
	s_waitcnt lgkmcnt(10)
	v_mfma_f32_32x32x16_bf16 v[32:47], v[214:217], v[52:55], v[32:47]
	s_waitcnt lgkmcnt(9)
	v_mfma_f32_32x32x16_bf16 v[32:47], v[210:213], v[56:59], v[32:47]
	s_waitcnt lgkmcnt(8)
	v_mfma_f32_32x32x16_bf16 v[32:47], v[130:133], v[60:63], v[32:47]
	s_nop 11
	v_min_f32_e64 v32, -v32, s60
	v_min_f32_e64 v33, -v33, s60
	v_exp_f32_e32 v32, v32
	v_min_f32_e64 v34, -v34, s60
	v_exp_f32_e32 v33, v33
	v_exp_f32_e32 v34, v34
	v_min_f32_e64 v35, -v35, s60
	v_exp_f32_e32 v130, v35
	v_add_f32_e32 v35, 1.0, v32
	v_add_f32_e32 v131, 1.0, v33
	v_rcp_f32_e32 v35, v35
	v_add_f32_e32 v132, 1.0, v34
	v_rcp_f32_e32 v131, v131
	v_min_f32_e64 v36, -v36, s60
	v_rcp_f32_e32 v132, v132
	v_exp_f32_e32 v36, v36
	v_add_f32_e32 v133, 1.0, v130
	v_rcp_f32_e32 v136, v133
	v_mul_f32_e32 v32, v32, v35
	v_mul_f32_e32 v133, v135, v35
	v_mul_f32_e32 v33, v33, v131
	v_mul_f32_e32 v137, v135, v131
	v_cndmask_b32_e32 v35, 1.0, v32, vcc
	v_cndmask_b32_e32 v138, 0, v133, vcc
	v_cmp_lt_i32_e32 vcc, 1, v134
	v_mul_f32_e32 v34, v34, v132
	v_mul_f32_e32 v32, v135, v132
	v_cndmask_b32_e32 v131, 1.0, v33, vcc
	v_cndmask_b32_e32 v137, 0, v137, vcc
	v_cmp_lt_i32_e32 vcc, 2, v134
	v_min_f32_e64 v39, -v39, s60
	v_cndmask_b32_e32 v33, 1.0, v34, vcc
	v_add_f32_e32 v34, 1.0, v36
	v_rcp_f32_e32 v34, v34
	v_cndmask_b32_e32 v139, 0, v32, vcc
	v_mul_f32_e32 v32, v130, v136
	v_cmp_lt_i32_e32 vcc, 3, v134
	v_exp_f32_e32 v39, v39
	v_cndmask_b32_e32 v133, 1.0, v32, vcc
	v_mul_f32_e32 v32, v135, v136
	v_cndmask_b32_e32 v136, 0, v32, vcc
	v_mul_f32_e32 v32, v36, v34
	v_min_f32_e64 v36, -v37, s60
	v_exp_f32_e32 v36, v36
	v_cmp_lt_i32_e32 vcc, 8, v134
	v_mul_f32_e32 v34, v135, v34
	v_cndmask_b32_e32 v140, 0, v34, vcc
	v_add_f32_e32 v34, 1.0, v36
	v_rcp_f32_e32 v34, v34
	v_min_f32_e64 v37, -v38, s60
	v_exp_f32_e32 v37, v37
	v_cndmask_b32_e32 v32, 1.0, v32, vcc
	v_mul_f32_e32 v36, v36, v34
	v_cmp_lt_i32_e32 vcc, 9, v134
	v_mul_f32_e32 v34, v135, v34
	v_min_f32_e64 v42, -v42, s60
	v_cndmask_b32_e32 v38, 1.0, v36, vcc
	v_add_f32_e32 v36, 1.0, v37
	v_rcp_f32_e32 v36, v36
	v_cndmask_b32_e32 v141, 0, v34, vcc
	v_cmp_lt_i32_e32 vcc, 10, v134
	v_exp_f32_e32 v42, v42
	v_mul_f32_e32 v34, v37, v36
	v_add_f32_e32 v37, 1.0, v39
	v_rcp_f32_e32 v37, v37
	v_cndmask_b32_e32 v142, 1.0, v34, vcc
	v_mul_f32_e32 v34, v135, v36
	v_cndmask_b32_e32 v143, 0, v34, vcc
	v_mul_f32_e32 v34, v39, v37
	v_cmp_lt_i32_e32 vcc, 11, v134
	v_min_f32_e64 v36, -v40, s60
	v_exp_f32_e32 v36, v36
	v_cndmask_b32_e32 v39, 1.0, v34, vcc
	v_mul_f32_e32 v34, v135, v37
	v_min_f32_e64 v37, -v41, s60
	v_exp_f32_e32 v37, v37
	v_cndmask_b32_e32 v40, 0, v34, vcc
	v_add_f32_e32 v34, 1.0, v36
	v_rcp_f32_e32 v34, v34
	v_add_f32_e32 v41, 1.0, v37
	v_rcp_f32_e32 v41, v41
	v_cmp_lt_i32_e32 vcc, 16, v134
	v_mul_f32_e32 v36, v36, v34
	v_mul_f32_e32 v34, v135, v34
	v_cndmask_b32_e32 v144, 0, v34, vcc
	v_mul_f32_e32 v34, v37, v41
	v_add_f32_e32 v37, 1.0, v42
	v_rcp_f32_e32 v37, v37
	v_cndmask_b32_e32 v36, 1.0, v36, vcc
	v_cmp_lt_i32_e32 vcc, 17, v134
	v_min_f32_e64 v45, -v45, s60
	v_cndmask_b32_e32 v145, 1.0, v34, vcc
	v_mul_f32_e32 v34, v135, v41
	v_cndmask_b32_e32 v41, 0, v34, vcc
	v_mul_f32_e32 v34, v42, v37
	v_cmp_lt_i32_e32 vcc, 18, v134
	v_min_f32_e64 v42, -v43, s60
	v_exp_f32_e32 v42, v42
	v_cndmask_b32_e32 v43, 1.0, v34, vcc
	v_mul_f32_e32 v34, v135, v37
	v_min_f32_e64 v37, -v44, s60
	v_exp_f32_e32 v37, v37
	v_cndmask_b32_e32 v146, 0, v34, vcc
	v_add_f32_e32 v34, 1.0, v42
	v_rcp_f32_e32 v34, v34
	v_add_f32_e32 v44, 1.0, v37
	v_rcp_f32_e32 v44, v44
	v_exp_f32_e32 v45, v45
	v_min_f32_e64 v46, -v46, s60
	v_min_f32_e64 v47, -v47, s60
	v_exp_f32_e32 v46, v46
	v_exp_f32_e32 v47, v47
	v_mul_f32_e32 v42, v42, v34
	v_cmp_lt_i32_e32 vcc, 19, v134
	v_mul_f32_e32 v34, v135, v34
	v_add_f32_e32 v130, 1.0, v46
	v_cndmask_b32_e32 v147, 0, v34, vcc
	v_mul_f32_e32 v34, v37, v44
	v_add_f32_e32 v37, 1.0, v45
	v_rcp_f32_e32 v37, v37
	v_add_f32_e32 v132, 1.0, v47
	v_rcp_f32_e32 v130, v130
	v_rcp_f32_e32 v132, v132
	v_cndmask_b32_e32 v42, 1.0, v42, vcc
	v_cmp_lt_i32_e32 vcc, 24, v134
	v_mul_f32_e32 v44, v135, v44
	v_mul_f32_e32 v45, v45, v37
	v_cndmask_b32_e32 v34, 1.0, v34, vcc
	v_cndmask_b32_e32 v44, 0, v44, vcc
	v_cmp_lt_i32_e32 vcc, 25, v134
	v_mul_f32_e32 v37, v135, v37
	v_mul_f32_e32 v46, v46, v130
	v_cndmask_b32_e32 v45, 1.0, v45, vcc
	v_cndmask_b32_e32 v37, 0, v37, vcc
	v_cmp_lt_i32_e32 vcc, 26, v134
	v_mul_f32_e32 v47, v47, v132
	v_cndmask_b32_e64 v47, 1.0, v47, s[0:1]
	v_cndmask_b32_e32 v46, 1.0, v46, vcc
	v_mul_f32_e32 v34, v34, v45
	v_mul_f32_e32 v134, v46, v47
	v_mul_f32_e32 v134, v34, v134
	v_mov_b32_e32 v148, v134
	v_mov_b32_e32 v240, v134
	s_nop 1
	v_permlane32_swap_b32_e32 v148, v240
	v_cndmask_b32_e64 v148, v148, v240, s[2:3]
	v_mul_f32_e32 v34, v135, v130
	v_cndmask_b32_e32 v149, 0, v34, vcc
	v_mul_f32_e32 v34, v135, v132
	v_cndmask_b32_e64 v34, 0, v34, s[0:1]
	s_waitcnt lgkmcnt(0)
; __device__ __forceinline__ void sb_unit(const Frame& F, int b, int hd, int qi, int dry) {
;     ...
;             float run = C;
;             if (!meta && key0 + 96 < tqw + 31) SB_HALF(96);
;             if (!meta && key0 + 64 < tqw + 31 && __any(run >= SB_DEAD)) SB_HALF(64);
;             if (!meta && key0 + 32 < tqw + 31 && __any(run >= SB_DEAD)) SB_HALF(32);
;             if (__any(run >= SB_DEAD)) SB_HALF(0);
	v_cndmask_b32_e64 v130, 1.0, v148, s[2:3]
	v_mul_f32_e32 v135, v34, v130
	v_mul_f32_e32 v34, v36, v145
	v_mul_f32_e32 v36, v43, v42
	v_mul_f32_e32 v36, v34, v36
	v_mul_f32_e32 v32, v32, v38
	v_mul_f32_e32 v34, v142, v39
	v_mov_b32_e32 v150, v36
	v_mov_b32_e32 v240, v36
	s_nop 1
	v_permlane32_swap_b32_e32 v150, v240
	v_cndmask_b32_e64 v150, v150, v240, s[2:3]
	v_mul_f32_e32 v34, v32, v34
	v_mul_f32_e32 v47, v47, v130
	v_mov_b32_e32 v130, v34
	v_mov_b32_e32 v240, v34
	s_nop 1
	v_permlane32_swap_b32_e32 v130, v240
	v_cndmask_b32_e64 v130, v130, v240, s[2:3]
	v_mul_f32_e32 v46, v46, v47
	v_mul_f32_e32 v32, v134, v148
	s_waitcnt lgkmcnt(1)
	v_mul_f32_e32 v132, v36, v150
	v_mul_f32_e32 v45, v45, v46
	v_mul_f32_e32 v46, v37, v46
	s_waitcnt lgkmcnt(0)
	v_cndmask_b32_e64 v134, 1.0, v130, s[2:3]
	v_pk_mul_f32 v[36:37], v[32:33], v[132:133]
	v_pk_mul_f32 v[34:35], v[34:35], v[130:131]
	v_mul_f32_e32 v132, v36, v134
	v_mul_f32_e32 v134, v39, v132
	v_mul_f32_e32 v142, v142, v134
	v_mul_f32_e32 v148, v38, v142
	v_pk_mul_f32 v[38:39], v[34:35], v[36:37]
	v_mov_b32_e32 v130, v39
	v_mov_b32_e32 v240, v39
	s_nop 1
	v_permlane32_swap_b32_e32 v130, v240
	v_cndmask_b32_e64 v130, v130, v240, s[2:3]
	v_mul_f32_e32 v37, v40, v132
	v_mul_f32_e32 v40, v143, v134
	v_mul_f32_e32 v36, v141, v142
	v_mul_f32_e32 v132, v140, v148
	s_waitcnt lgkmcnt(0)
	v_cndmask_b32_e64 v34, 1.0, v130, s[2:3]
	v_mul_f32_e32 v34, v38, v34
	v_mul_f32_e32 v35, v133, v34
	v_mul_f32_e32 v33, v33, v35
	v_mul_f32_e32 v131, v131, v33
	v_mul_f32_e32 v133, v136, v34
	v_mul_f32_e32 v35, v139, v35
	v_mul_f32_e32 v33, v137, v33
	v_mul_f32_e32 v34, v138, v131
	v_cvt_pk_bf16_f32 v34, v34, v33
	v_cvt_pk_bf16_f32 v35, v35, v133
	v_cvt_pk_bf16_f32 v36, v132, v36
	v_cvt_pk_bf16_f32 v37, v40, v37
	v_cndmask_b32_e64 v33, 1.0, v150, s[2:3]
	v_mul_f32_e32 v32, v32, v33
	v_mfma_f32_32x32x16_bf16 v[16:31], v[92:95], v[34:37], v[16:31]
	v_mul_f32_e32 v33, v42, v32
	v_mul_f32_e32 v42, v43, v33
	v_mul_f32_e32 v43, v145, v42
	v_mul_f32_e32 v47, v149, v47
	v_mul_f32_e32 v40, v44, v45
	v_mul_f32_e32 v44, v147, v32
	v_mul_f32_e32 v33, v146, v33
	v_mfma_f32_32x32x16_bf16 v[0:15], v[88:91], v[34:37], v[0:15]
	v_mul_f32_e32 v32, v41, v42
	v_mul_f32_e32 v34, v144, v43
	v_cvt_pk_bf16_f32 v32, v34, v32
	v_cvt_pk_bf16_f32 v33, v33, v44
	v_cvt_pk_bf16_f32 v34, v40, v46
	v_cvt_pk_bf16_f32 v35, v47, v135
	v_mul_f32_e32 v36, v39, v130
	v_mul_f32_e32 v36, v38, v36
	v_mfma_f32_32x32x16_bf16 v[16:31], v[84:87], v[32:35], v[16:31]
	v_log_f32_e32 v36, v36
	s_nop 0
	v_add_f32_e32 v125, v125, v36
	v_mfma_f32_32x32x16_bf16 v[0:15], v[80:83], v[32:35], v[0:15]
.LBB0_347:
	v_cmp_le_f32_e32 vcc, s22, v125
	s_cbranch_vccz .LBB0_349
	ds_read_b128 v[32:35], v129
	ds_read_b128 v[214:217], v129 offset:32
	ds_read_b128 v[210:213], v129 offset:64
	ds_read_b128 v[130:133], v129 offset:96
	ds_read_b64_tr_b16 v[92:93], v128 offset:36864
	ds_read_b64_tr_b16 v[94:95], v128 offset:38400
	ds_read_b64_tr_b16 v[90:91], v128 offset:38464
	ds_read_b64_tr_b16 v[88:89], v128 offset:36928
	ds_read_b64_tr_b16 v[84:85], v128 offset:39936
	ds_read_b64_tr_b16 v[86:87], v128 offset:41472
	ds_read_b64_tr_b16 v[82:83], v128 offset:41536
	ds_read_b64_tr_b16 v[80:81], v128 offset:40000
	v_cndmask_b32_e64 v129, v114, 16, s[18:19]
	v_sub_u32_e32 v127, v129, v127
	v_cmp_lt_i32_e32 vcc, 0, v127
	v_cmp_lt_i32_e64 s[0:1], 27, v127
	v_exp_f32_e32 v128, v125
	s_waitcnt lgkmcnt(11)
	v_mfma_f32_32x32x16_bf16 v[32:47], v[32:35], v[48:51], 0
	s_waitcnt lgkmcnt(10)
	v_mfma_f32_32x32x16_bf16 v[32:47], v[214:217], v[52:55], v[32:47]
	s_waitcnt lgkmcnt(9)
	v_mfma_f32_32x32x16_bf16 v[32:47], v[210:213], v[56:59], v[32:47]
	s_waitcnt lgkmcnt(8)
	v_mfma_f32_32x32x16_bf16 v[32:47], v[130:133], v[60:63], v[32:47]
	s_nop 11
	v_min_f32_e64 v32, -v32, s60
	v_min_f32_e64 v33, -v33, s60
	v_exp_f32_e32 v32, v32
	v_min_f32_e64 v34, -v34, s60
	v_exp_f32_e32 v33, v33
	v_exp_f32_e32 v34, v34
	v_min_f32_e64 v35, -v35, s60
	v_exp_f32_e32 v130, v35
	v_add_f32_e32 v35, 1.0, v32
	v_add_f32_e32 v129, 1.0, v33
	v_rcp_f32_e32 v35, v35
	v_add_f32_e32 v131, 1.0, v34
	v_rcp_f32_e32 v129, v129
	v_rcp_f32_e32 v131, v131
	v_add_f32_e32 v132, 1.0, v130
	v_rcp_f32_e32 v132, v132
	v_mul_f32_e32 v32, v32, v35
	v_mul_f32_e32 v133, v128, v35
	v_min_f32_e64 v36, -v36, s60
	v_mul_f32_e32 v33, v33, v129
	v_mul_f32_e32 v134, v128, v129
	v_cndmask_b32_e32 v35, 1.0, v32, vcc
	v_cndmask_b32_e32 v133, 0, v133, vcc
	v_cmp_lt_i32_e32 vcc, 1, v127
	v_mul_f32_e32 v34, v34, v131
	v_exp_f32_e32 v32, v36
	v_cndmask_b32_e32 v129, 1.0, v33, vcc
	v_cndmask_b32_e32 v134, 0, v134, vcc
	v_cmp_lt_i32_e32 vcc, 2, v127
	v_add_f32_e32 v36, 1.0, v32
	v_rcp_f32_e32 v36, v36
	v_cndmask_b32_e32 v33, 1.0, v34, vcc
	v_mul_f32_e32 v34, v128, v131
	v_cndmask_b32_e32 v135, 0, v34, vcc
	v_mul_f32_e32 v34, v130, v132
	v_cmp_lt_i32_e32 vcc, 3, v127
	v_mul_f32_e32 v32, v32, v36
	v_mul_f32_e32 v36, v128, v36
	v_cndmask_b32_e32 v131, 1.0, v34, vcc
	v_mul_f32_e32 v34, v128, v132
	v_cndmask_b32_e32 v132, 0, v34, vcc
	v_min_f32_e64 v34, -v37, s60
	v_exp_f32_e32 v34, v34
	v_cmp_lt_i32_e32 vcc, 8, v127
	v_min_f32_e64 v37, -v38, s60
	v_cndmask_b32_e32 v136, 0, v36, vcc
	v_add_f32_e32 v36, 1.0, v34
	v_rcp_f32_e32 v36, v36
	v_exp_f32_e32 v37, v37
	v_cndmask_b32_e32 v32, 1.0, v32, vcc
	v_cmp_lt_i32_e32 vcc, 9, v127
	v_mul_f32_e32 v34, v34, v36
	v_cndmask_b32_e32 v38, 1.0, v34, vcc
	v_add_f32_e32 v34, 1.0, v37
	v_min_f32_e64 v39, -v39, s60
	v_rcp_f32_e32 v34, v34
	v_exp_f32_e32 v39, v39
	v_mul_f32_e32 v36, v128, v36
	v_cndmask_b32_e32 v137, 0, v36, vcc
	v_mul_f32_e32 v36, v37, v34
	v_add_f32_e32 v37, 1.0, v39
	v_rcp_f32_e32 v37, v37
	v_cmp_lt_i32_e32 vcc, 10, v127
	v_mul_f32_e32 v34, v128, v34
	v_cndmask_b32_e32 v138, 1.0, v36, vcc
	v_cndmask_b32_e32 v139, 0, v34, vcc
	v_mul_f32_e32 v34, v39, v37
	v_cmp_lt_i32_e32 vcc, 11, v127
	v_min_f32_e64 v36, -v40, s60
	v_exp_f32_e32 v36, v36
	v_cndmask_b32_e32 v39, 1.0, v34, vcc
	v_mul_f32_e32 v34, v128, v37
	v_min_f32_e64 v37, -v41, s60
	v_exp_f32_e32 v37, v37
	v_cndmask_b32_e32 v40, 0, v34, vcc
	v_add_f32_e32 v34, 1.0, v36
	v_rcp_f32_e32 v34, v34
	v_add_f32_e32 v41, 1.0, v37
	v_min_f32_e64 v42, -v42, s60
	v_rcp_f32_e32 v41, v41
	v_exp_f32_e32 v42, v42
	v_mul_f32_e32 v36, v36, v34
	v_cmp_lt_i32_e32 vcc, 16, v127
	v_mul_f32_e32 v34, v128, v34
	v_cndmask_b32_e32 v140, 0, v34, vcc
	v_mul_f32_e32 v34, v37, v41
	v_add_f32_e32 v37, 1.0, v42
	v_rcp_f32_e32 v37, v37
	v_cndmask_b32_e32 v36, 1.0, v36, vcc
	v_cmp_lt_i32_e32 vcc, 17, v127
	v_min_f32_e64 v45, -v45, s60
	v_cndmask_b32_e32 v141, 1.0, v34, vcc
	v_mul_f32_e32 v34, v128, v41
	v_cndmask_b32_e32 v41, 0, v34, vcc
	v_mul_f32_e32 v34, v42, v37
	v_cmp_lt_i32_e32 vcc, 18, v127
	v_min_f32_e64 v42, -v43, s60
	v_exp_f32_e32 v42, v42
	v_cndmask_b32_e32 v43, 1.0, v34, vcc
	v_mul_f32_e32 v34, v128, v37
	v_min_f32_e64 v37, -v44, s60
	v_exp_f32_e32 v37, v37
	v_cndmask_b32_e32 v142, 0, v34, vcc
	v_add_f32_e32 v34, 1.0, v42
	v_rcp_f32_e32 v34, v34
	v_add_f32_e32 v44, 1.0, v37
	v_rcp_f32_e32 v44, v44
	v_exp_f32_e32 v45, v45
	v_min_f32_e64 v46, -v46, s60
	v_min_f32_e64 v47, -v47, s60
	v_exp_f32_e32 v46, v46
	v_exp_f32_e32 v47, v47
	v_mul_f32_e32 v42, v42, v34
	v_cmp_lt_i32_e32 vcc, 19, v127
	v_mul_f32_e32 v34, v128, v34
	v_add_f32_e32 v130, 1.0, v46
	v_cndmask_b32_e32 v143, 0, v34, vcc
	v_mul_f32_e32 v34, v37, v44
	v_add_f32_e32 v37, 1.0, v45
	v_rcp_f32_e32 v37, v37
	v_add_f32_e32 v144, 1.0, v47
	v_rcp_f32_e32 v130, v130
	v_rcp_f32_e32 v144, v144
	v_cndmask_b32_e32 v42, 1.0, v42, vcc
	v_cmp_lt_i32_e32 vcc, 24, v127
	v_mul_f32_e32 v44, v128, v44
	v_mul_f32_e32 v45, v45, v37
	v_cndmask_b32_e32 v34, 1.0, v34, vcc
	v_cndmask_b32_e32 v44, 0, v44, vcc
	v_cmp_lt_i32_e32 vcc, 25, v127
	v_mul_f32_e32 v37, v128, v37
	v_mul_f32_e32 v46, v46, v130
	v_cndmask_b32_e32 v45, 1.0, v45, vcc
	v_cndmask_b32_e32 v37, 0, v37, vcc
	v_cmp_lt_i32_e32 vcc, 26, v127
	v_mul_f32_e32 v47, v47, v144
	v_cndmask_b32_e64 v47, 1.0, v47, s[0:1]
	v_cndmask_b32_e32 v46, 1.0, v46, vcc
	v_mul_f32_e32 v34, v34, v45
	v_mul_f32_e32 v127, v46, v47
	v_mul_f32_e32 v127, v34, v127
	v_mov_b32_e32 v145, v127
	v_mov_b32_e32 v240, v127
	s_nop 1
	v_permlane32_swap_b32_e32 v145, v240
	v_cndmask_b32_e64 v145, v145, v240, s[2:3]
	v_mul_f32_e32 v34, v128, v130
	v_cndmask_b32_e32 v130, 0, v34, vcc
	v_mul_f32_e32 v34, v128, v144
	v_cndmask_b32_e64 v34, 0, v34, s[0:1]
	s_waitcnt lgkmcnt(0)
	v_cndmask_b32_e64 v128, 1.0, v145, s[2:3]
	v_mul_f32_e32 v144, v34, v128
	v_mul_f32_e32 v34, v36, v141
	v_mul_f32_e32 v36, v43, v42
	v_mul_f32_e32 v36, v34, v36
	v_mul_f32_e32 v32, v32, v38
	v_mul_f32_e32 v34, v138, v39
	v_mov_b32_e32 v146, v36
	v_mov_b32_e32 v240, v36
	s_nop 1
	v_permlane32_swap_b32_e32 v146, v240
	v_cndmask_b32_e64 v146, v146, v240, s[2:3]
	v_mul_f32_e32 v34, v32, v34
	v_mul_f32_e32 v47, v47, v128
	v_mov_b32_e32 v128, v34
	v_mov_b32_e32 v240, v34
	s_nop 1
	v_permlane32_swap_b32_e32 v128, v240
	v_cndmask_b32_e64 v128, v128, v240, s[2:3]
	v_mul_f32_e32 v46, v46, v47
	v_mul_f32_e32 v47, v130, v47
	v_mul_f32_e32 v32, v127, v145
	s_waitcnt lgkmcnt(1)
	v_mul_f32_e32 v130, v36, v146
	v_mul_f32_e32 v45, v45, v46
	v_mul_f32_e32 v46, v37, v46
	s_waitcnt lgkmcnt(0)
	v_cndmask_b32_e64 v127, 1.0, v128, s[2:3]
	v_pk_mul_f32 v[36:37], v[32:33], v[130:131]
	v_pk_mul_f32 v[34:35], v[34:35], v[128:129]
	v_mul_f32_e32 v127, v36, v127
	v_mul_f32_e32 v130, v39, v127
	v_mul_f32_e32 v138, v138, v130
	v_mul_f32_e32 v145, v38, v138
	v_pk_mul_f32 v[38:39], v[34:35], v[36:37]
	v_mov_b32_e32 v128, v39
	v_mov_b32_e32 v240, v39
	s_nop 1
	v_permlane32_swap_b32_e32 v128, v240
	v_cndmask_b32_e64 v128, v128, v240, s[2:3]
	v_mul_f32_e32 v37, v40, v127
	v_mul_f32_e32 v40, v139, v130
	v_mul_f32_e32 v36, v137, v138
	v_mul_f32_e32 v127, v136, v145
	s_waitcnt lgkmcnt(0)
	v_cndmask_b32_e64 v34, 1.0, v128, s[2:3]
	v_mul_f32_e32 v34, v38, v34
	v_mul_f32_e32 v35, v131, v34
	v_mul_f32_e32 v33, v33, v35
	v_mul_f32_e32 v129, v129, v33
	v_mul_f32_e32 v130, v132, v34
	v_mul_f32_e32 v35, v135, v35
	v_mul_f32_e32 v33, v134, v33
	v_mul_f32_e32 v34, v133, v129
	v_cvt_pk_bf16_f32 v34, v34, v33
	v_cvt_pk_bf16_f32 v35, v35, v130
	v_cvt_pk_bf16_f32 v36, v127, v36
	v_cvt_pk_bf16_f32 v37, v40, v37
	v_cndmask_b32_e64 v33, 1.0, v146, s[2:3]
	v_mul_f32_e32 v32, v32, v33
	v_mfma_f32_32x32x16_bf16 v[16:31], v[92:95], v[34:37], v[16:31]
	v_mul_f32_e32 v33, v42, v32
	v_mul_f32_e32 v42, v43, v33
	v_mul_f32_e32 v43, v141, v42
	v_mul_f32_e32 v40, v44, v45
	v_mul_f32_e32 v44, v143, v32
	v_mul_f32_e32 v33, v142, v33
	v_mul_f32_e32 v32, v41, v42
	v_mfma_f32_32x32x16_bf16 v[0:15], v[88:91], v[34:37], v[0:15]
	v_mul_f32_e32 v34, v140, v43
	v_cvt_pk_bf16_f32 v32, v34, v32
	v_cvt_pk_bf16_f32 v33, v33, v44
	v_cvt_pk_bf16_f32 v34, v40, v46
	v_cvt_pk_bf16_f32 v35, v47, v144
	v_mul_f32_e32 v36, v39, v128
	v_mul_f32_e32 v36, v38, v36
	v_mfma_f32_32x32x16_bf16 v[16:31], v[84:87], v[32:35], v[16:31]
	v_log_f32_e32 v36, v36
	s_nop 0
	v_add_f32_e32 v125, v125, v36
	v_mfma_f32_32x32x16_bf16 v[0:15], v[80:83], v[32:35], v[0:15]

; #define LAS __attribute__((address_space(3)))
; #define S_LOAD(key0) do { st0 = *(const u32x4*)(kg + (size_t)(key0) * 1024); st1 = *(const u32x4*)(kg + (size_t)((key0) + 64) * 1024); st2 = *(const u32x4*)(vg + (size_t)(key0) * 1024); st3 = *(const u32x4*)(vg + (size_t)((key0) + 64) * 1024); } while (0)
; __device__ __forceinline__ void sb_unit(const Frame& F, int b, int hd, int qi, int dry) {
;     ...
;     for (int it = 0; it < nt; ++it) {
;         const bool meta = (it > jmax);
;         const int key0 = meta ? 0 : NMETA + 128 * (jmax - it);
;         if (it + 1 < nt) { const int nk = (it + 1 > jmax) ? 0 : NMETA + 128 * (jmax - it - 1); S_LOAD(nk); }
;         if (!dead && (meta || key0 < tqw + 31)) {
;             const LAS unsigned char* kb = lds + kra + (it & 1) * SK_BUF;
;             const LAS unsigned char* vb = lds + vra + (it & 1) * SV_BUF;
;     ...
;             float run = C;
;             if (!meta && key0 + 96 < tqw + 31) SB_HALF(96);
.LBB0_360:
	s_xor_b64 s[0:1], s[0:1], -1
	s_andn2_b64 vcc, exec, s[0:1]
	s_mov_b64 s[0:1], -1
	s_cbranch_vccnz .LBB0_373
	s_add_i32 s34, s31, 0xffffff10
	s_cmp_gt_u32 s35, s27
	s_cselect_b64 s[18:19], -1, 0
	s_and_b64 s[0:1], s[18:19], exec
	s_cselect_b32 s34, 0, s34
	s_cmp_lt_i32 s34, s29
	s_cselect_b64 s[0:1], -1, 0
	s_or_b64 s[0:1], s[18:19], s[0:1]
	s_andn2_b64 vcc, exec, s[0:1]
	s_mov_b64 s[0:1], 0
	s_cbranch_vccnz .LBB0_373
	s_and_b32 s0, s35, 1
	s_mul_i32 s35, s0, 0x4800
	s_mul_i32 s36, s0, 0x6000
	s_or_b32 s0, s34, 0x41
	s_cmp_ge_i32 s0, s25
	s_cselect_b64 s[0:1], -1, 0
	s_or_b64 s[0:1], s[18:19], s[0:1]
	s_and_b64 vcc, exec, s[0:1]
	v_add_u32_e32 v129, s35, v118
	v_or_b32_e32 v127, s34, v205
	v_add_u32_e32 v128, s36, v119
	s_cbranch_vccnz .LBB0_364
	ds_read_b128 v[32:35], v129 offset:13824
	ds_read_b128 v[214:217], v129 offset:13856
	ds_read_b128 v[210:213], v129 offset:13888
	ds_read_b128 v[130:133], v129 offset:13920
	ds_read_b64_tr_b16 v[92:93], v128 offset:55296
	ds_read_b64_tr_b16 v[94:95], v128 offset:56832
	ds_read_b64_tr_b16 v[90:91], v128 offset:56896
	ds_read_b64_tr_b16 v[88:89], v128 offset:55360
	ds_read_b64_tr_b16 v[84:85], v128 offset:58368
	ds_read_b64_tr_b16 v[86:87], v128 offset:59904
	ds_read_b64_tr_b16 v[82:83], v128 offset:59968
	ds_read_b64_tr_b16 v[80:81], v128 offset:58432
	v_exp_f32_e32 v135, v126
	v_sub_u32_e32 v134, v115, v127
	v_cmp_lt_i32_e32 vcc, 0, v134
	s_waitcnt lgkmcnt(11)
	v_mfma_f32_32x32x16_bf16 v[32:47], v[32:35], v[48:51], 0
	v_cmp_lt_i32_e64 s[0:1], 27, v134
	s_waitcnt lgkmcnt(10)
	v_mfma_f32_32x32x16_bf16 v[32:47], v[214:217], v[52:55], v[32:47]
	s_waitcnt lgkmcnt(9)
	v_mfma_f32_32x32x16_bf16 v[32:47], v[210:213], v[56:59], v[32:47]
	s_waitcnt lgkmcnt(8)
	v_mfma_f32_32x32x16_bf16 v[32:47], v[130:133], v[60:63], v[32:47]
	s_nop 11
	v_min_f32_e64 v32, -v32, s60
	v_min_f32_e64 v33, -v33, s60
	v_exp_f32_e32 v32, v32
	v_min_f32_e64 v34, -v34, s60
	v_exp_f32_e32 v33, v33
	v_exp_f32_e32 v34, v34
	v_min_f32_e64 v35, -v35, s60
	v_exp_f32_e32 v130, v35
	v_add_f32_e32 v35, 1.0, v32
	v_add_f32_e32 v131, 1.0, v33
	v_rcp_f32_e32 v35, v35
	v_add_f32_e32 v132, 1.0, v34
	v_rcp_f32_e32 v131, v131
	v_min_f32_e64 v36, -v36, s60
	v_rcp_f32_e32 v132, v132
	v_exp_f32_e32 v36, v36
	v_add_f32_e32 v133, 1.0, v130
	v_rcp_f32_e32 v136, v133
	v_mul_f32_e32 v32, v32, v35
	v_mul_f32_e32 v133, v135, v35
	v_mul_f32_e32 v33, v33, v131
	v_mul_f32_e32 v137, v135, v131
	v_cndmask_b32_e32 v35, 1.0, v32, vcc
	v_cndmask_b32_e32 v138, 0, v133, vcc
	v_cmp_lt_i32_e32 vcc, 1, v134
	v_mul_f32_e32 v34, v34, v132
	v_mul_f32_e32 v32, v135, v132
	v_cndmask_b32_e32 v131, 1.0, v33, vcc
	v_cndmask_b32_e32 v137, 0, v137, vcc
	v_cmp_lt_i32_e32 vcc, 2, v134
	v_min_f32_e64 v39, -v39, s60
	v_cndmask_b32_e32 v33, 1.0, v34, vcc
	v_add_f32_e32 v34, 1.0, v36
	v_rcp_f32_e32 v34, v34
	v_cndmask_b32_e32 v139, 0, v32, vcc
	v_mul_f32_e32 v32, v130, v136
	v_cmp_lt_i32_e32 vcc, 3, v134
	v_exp_f32_e32 v39, v39
	v_cndmask_b32_e32 v133, 1.0, v32, vcc
	v_mul_f32_e32 v32, v135, v136
	v_cndmask_b32_e32 v136, 0, v32, vcc
	v_mul_f32_e32 v32, v36, v34
	v_min_f32_e64 v36, -v37, s60
	v_exp_f32_e32 v36, v36
	v_cmp_lt_i32_e32 vcc, 8, v134
	v_mul_f32_e32 v34, v135, v34
	v_cndmask_b32_e32 v140, 0, v34, vcc
	v_add_f32_e32 v34, 1.0, v36
	v_rcp_f32_e32 v34, v34
	v_min_f32_e64 v37, -v38, s60
	v_exp_f32_e32 v37, v37
	v_cndmask_b32_e32 v32, 1.0, v32, vcc
	v_mul_f32_e32 v36, v36, v34
	v_cmp_lt_i32_e32 vcc, 9, v134
	v_mul_f32_e32 v34, v135, v34
	v_min_f32_e64 v42, -v42, s60
	v_cndmask_b32_e32 v38, 1.0, v36, vcc
	v_add_f32_e32 v36, 1.0, v37
	v_rcp_f32_e32 v36, v36
	v_cndmask_b32_e32 v141, 0, v34, vcc
	v_cmp_lt_i32_e32 vcc, 10, v134
	v_exp_f32_e32 v42, v42
	v_mul_f32_e32 v34, v37, v36
	v_add_f32_e32 v37, 1.0, v39
	v_rcp_f32_e32 v37, v37
	v_cndmask_b32_e32 v142, 1.0, v34, vcc
	v_mul_f32_e32 v34, v135, v36
	v_cndmask_b32_e32 v143, 0, v34, vcc
	v_mul_f32_e32 v34, v39, v37
	v_cmp_lt_i32_e32 vcc, 11, v134
	v_min_f32_e64 v36, -v40, s60
	v_exp_f32_e32 v36, v36
	v_cndmask_b32_e32 v39, 1.0, v34, vcc
	v_mul_f32_e32 v34, v135, v37
	v_min_f32_e64 v37, -v41, s60
	v_exp_f32_e32 v37, v37
	v_cndmask_b32_e32 v40, 0, v34, vcc
	v_add_f32_e32 v34, 1.0, v36
	v_rcp_f32_e32 v34, v34
	v_add_f32_e32 v41, 1.0, v37
	v_rcp_f32_e32 v41, v41
	v_cmp_lt_i32_e32 vcc, 16, v134
	v_mul_f32_e32 v36, v36, v34
	v_mul_f32_e32 v34, v135, v34
	v_cndmask_b32_e32 v144, 0, v34, vcc
	v_mul_f32_e32 v34, v37, v41
	v_add_f32_e32 v37, 1.0, v42
	v_rcp_f32_e32 v37, v37
	v_cndmask_b32_e32 v36, 1.0, v36, vcc
	v_cmp_lt_i32_e32 vcc, 17, v134
	v_min_f32_e64 v45, -v45, s60
	v_cndmask_b32_e32 v145, 1.0, v34, vcc
	v_mul_f32_e32 v34, v135, v41
	v_cndmask_b32_e32 v41, 0, v34, vcc
	v_mul_f32_e32 v34, v42, v37
	v_cmp_lt_i32_e32 vcc, 18, v134
	v_min_f32_e64 v42, -v43, s60
	v_exp_f32_e32 v42, v42
	v_cndmask_b32_e32 v43, 1.0, v34, vcc
	v_mul_f32_e32 v34, v135, v37
	v_min_f32_e64 v37, -v44, s60
	v_exp_f32_e32 v37, v37
	v_cndmask_b32_e32 v146, 0, v34, vcc
	v_add_f32_e32 v34, 1.0, v42
	v_rcp_f32_e32 v34, v34
	v_add_f32_e32 v44, 1.0, v37
	v_rcp_f32_e32 v44, v44
	v_exp_f32_e32 v45, v45
	v_min_f32_e64 v46, -v46, s60
	v_min_f32_e64 v47, -v47, s60
	v_exp_f32_e32 v46, v46
	v_exp_f32_e32 v47, v47
	v_mul_f32_e32 v42, v42, v34
	v_cmp_lt_i32_e32 vcc, 19, v134
	v_mul_f32_e32 v34, v135, v34
	v_add_f32_e32 v130, 1.0, v46
	v_cndmask_b32_e32 v147, 0, v34, vcc
	v_mul_f32_e32 v34, v37, v44
	v_add_f32_e32 v37, 1.0, v45
	v_rcp_f32_e32 v37, v37
	v_add_f32_e32 v132, 1.0, v47
	v_rcp_f32_e32 v130, v130
	v_rcp_f32_e32 v132, v132
	v_cndmask_b32_e32 v42, 1.0, v42, vcc
	v_cmp_lt_i32_e32 vcc, 24, v134
	v_mul_f32_e32 v44, v135, v44
	v_mul_f32_e32 v45, v45, v37
	v_cndmask_b32_e32 v34, 1.0, v34, vcc
	v_cndmask_b32_e32 v44, 0, v44, vcc
	v_cmp_lt_i32_e32 vcc, 25, v134
	v_mul_f32_e32 v37, v135, v37
	v_mul_f32_e32 v46, v46, v130
	v_cndmask_b32_e32 v45, 1.0, v45, vcc
	v_cndmask_b32_e32 v37, 0, v37, vcc
	v_cmp_lt_i32_e32 vcc, 26, v134
	v_mul_f32_e32 v47, v47, v132
	v_cndmask_b32_e64 v47, 1.0, v47, s[0:1]
	v_cndmask_b32_e32 v46, 1.0, v46, vcc
	v_mul_f32_e32 v34, v34, v45
	v_mul_f32_e32 v134, v46, v47
	v_mul_f32_e32 v134, v34, v134
	v_mov_b32_e32 v148, v134
	v_mov_b32_e32 v240, v134
	s_nop 1
	v_permlane32_swap_b32_e32 v148, v240
	v_cndmask_b32_e64 v148, v148, v240, s[2:3]
	v_mul_f32_e32 v34, v135, v130
	v_cndmask_b32_e32 v149, 0, v34, vcc
	v_mul_f32_e32 v34, v135, v132
	v_cndmask_b32_e64 v34, 0, v34, s[0:1]
	s_waitcnt lgkmcnt(0)
; __device__ __forceinline__ void sb_unit(const Frame& F, int b, int hd, int qi, int dry) {
;     ...
;             float run = C;
;             if (!meta && key0 + 96 < tqw + 31) SB_HALF(96);
;             if (!meta && key0 + 64 < tqw + 31 && __any(run >= SB_DEAD)) SB_HALF(64);
	v_cndmask_b32_e64 v130, 1.0, v148, s[2:3]
	v_mul_f32_e32 v135, v34, v130
	v_mul_f32_e32 v34, v36, v145
	v_mul_f32_e32 v36, v43, v42
	v_mul_f32_e32 v36, v34, v36
	v_mul_f32_e32 v32, v32, v38
	v_mul_f32_e32 v34, v142, v39
	v_mov_b32_e32 v150, v36
	v_mov_b32_e32 v240, v36
	s_nop 1
	v_permlane32_swap_b32_e32 v150, v240
	v_cndmask_b32_e64 v150, v150, v240, s[2:3]
	v_mul_f32_e32 v34, v32, v34
	v_mul_f32_e32 v47, v47, v130
	v_mov_b32_e32 v130, v34
	v_mov_b32_e32 v240, v34
	s_nop 1
	v_permlane32_swap_b32_e32 v130, v240
	v_cndmask_b32_e64 v130, v130, v240, s[2:3]
	v_mul_f32_e32 v46, v46, v47
	v_mul_f32_e32 v32, v134, v148
	s_waitcnt lgkmcnt(1)
	v_mul_f32_e32 v132, v36, v150
	v_mul_f32_e32 v45, v45, v46
	v_mul_f32_e32 v46, v37, v46
	s_waitcnt lgkmcnt(0)
	v_cndmask_b32_e64 v134, 1.0, v130, s[2:3]
	v_pk_mul_f32 v[36:37], v[32:33], v[132:133]
	v_pk_mul_f32 v[34:35], v[34:35], v[130:131]
	v_mul_f32_e32 v132, v36, v134
	v_mul_f32_e32 v134, v39, v132
	v_mul_f32_e32 v142, v142, v134
	v_mul_f32_e32 v148, v38, v142
	v_pk_mul_f32 v[38:39], v[34:35], v[36:37]
	v_mov_b32_e32 v130, v39
	v_mov_b32_e32 v240, v39
	s_nop 1
	v_permlane32_swap_b32_e32 v130, v240
	v_cndmask_b32_e64 v130, v130, v240, s[2:3]
	v_mul_f32_e32 v37, v40, v132
	v_mul_f32_e32 v40, v143, v134
	v_mul_f32_e32 v36, v141, v142
	v_mul_f32_e32 v132, v140, v148
	s_waitcnt lgkmcnt(0)
	v_cndmask_b32_e64 v34, 1.0, v130, s[2:3]
	v_mul_f32_e32 v34, v38, v34
	v_mul_f32_e32 v35, v133, v34
	v_mul_f32_e32 v33, v33, v35
	v_mul_f32_e32 v131, v131, v33
	v_mul_f32_e32 v133, v136, v34
	v_mul_f32_e32 v35, v139, v35
	v_mul_f32_e32 v33, v137, v33
	v_mul_f32_e32 v34, v138, v131
	v_cvt_pk_bf16_f32 v34, v34, v33
	v_cvt_pk_bf16_f32 v35, v35, v133
	v_cvt_pk_bf16_f32 v36, v132, v36
	v_cvt_pk_bf16_f32 v37, v40, v37
	v_cndmask_b32_e64 v33, 1.0, v150, s[2:3]
	v_mul_f32_e32 v32, v32, v33
	v_mfma_f32_32x32x16_bf16 v[0:15], v[92:95], v[34:37], v[0:15]
	v_mul_f32_e32 v33, v42, v32
	v_mul_f32_e32 v42, v43, v33
	v_mul_f32_e32 v43, v145, v42
	v_mul_f32_e32 v47, v149, v47
	v_mul_f32_e32 v40, v44, v45
	v_mul_f32_e32 v44, v147, v32
	v_mul_f32_e32 v33, v146, v33
	v_mfma_f32_32x32x16_bf16 v[16:31], v[88:91], v[34:37], v[16:31]
	v_mul_f32_e32 v32, v41, v42
	v_mul_f32_e32 v34, v144, v43
	v_cvt_pk_bf16_f32 v32, v34, v32
	v_cvt_pk_bf16_f32 v33, v33, v44
	v_cvt_pk_bf16_f32 v34, v40, v46
	v_cvt_pk_bf16_f32 v35, v47, v135
	v_mul_f32_e32 v36, v39, v130
	v_mul_f32_e32 v36, v38, v36
	v_mfma_f32_32x32x16_bf16 v[0:15], v[84:87], v[32:35], v[0:15]
	v_log_f32_e32 v36, v36
	s_nop 0
	v_add_f32_e32 v126, v126, v36
	v_mfma_f32_32x32x16_bf16 v[16:31], v[80:83], v[32:35], v[16:31]
.LBB0_364:
	s_or_b32 s0, s34, 33
	s_cmp_ge_i32 s0, s25
	s_cselect_b64 s[0:1], -1, 0
	s_or_b64 s[0:1], s[18:19], s[0:1]
	s_and_b64 vcc, exec, s[0:1]
	s_cbranch_vccnz .LBB0_367
	v_cmp_le_f32_e32 vcc, s22, v126
	s_cbranch_vccz .LBB0_367
	ds_read_b128 v[32:35], v129 offset:9216
	ds_read_b128 v[214:217], v129 offset:9248
	ds_read_b128 v[210:213], v129 offset:9280
	ds_read_b128 v[130:133], v129 offset:9312
	ds_read_b64_tr_b16 v[92:93], v128 offset:49152
	ds_read_b64_tr_b16 v[94:95], v128 offset:50688
	ds_read_b64_tr_b16 v[90:91], v128 offset:50752
	ds_read_b64_tr_b16 v[88:89], v128 offset:49216
	ds_read_b64_tr_b16 v[84:85], v128 offset:52224
	ds_read_b64_tr_b16 v[86:87], v128 offset:53760
	ds_read_b64_tr_b16 v[82:83], v128 offset:53824
	ds_read_b64_tr_b16 v[80:81], v128 offset:52288
	v_exp_f32_e32 v135, v126
	v_sub_u32_e32 v134, v124, v127
	v_cmp_lt_i32_e32 vcc, 0, v134
	s_waitcnt lgkmcnt(11)
	v_mfma_f32_32x32x16_bf16 v[32:47], v[32:35], v[48:51], 0
	v_cmp_lt_i32_e64 s[0:1], 27, v134
	s_waitcnt lgkmcnt(10)
	v_mfma_f32_32x32x16_bf16 v[32:47], v[214:217], v[52:55], v[32:47]
	s_waitcnt lgkmcnt(9)
	v_mfma_f32_32x32x16_bf16 v[32:47], v[210:213], v[56:59], v[32:47]
	s_waitcnt lgkmcnt(8)
	v_mfma_f32_32x32x16_bf16 v[32:47], v[130:133], v[60:63], v[32:47]
	s_nop 11
	v_min_f32_e64 v32, -v32, s60
	v_min_f32_e64 v33, -v33, s60
	v_exp_f32_e32 v32, v32
	v_min_f32_e64 v34, -v34, s60
	v_exp_f32_e32 v33, v33
	v_exp_f32_e32 v34, v34
	v_min_f32_e64 v35, -v35, s60
	v_exp_f32_e32 v130, v35
	v_add_f32_e32 v35, 1.0, v32
	v_add_f32_e32 v131, 1.0, v33
	v_rcp_f32_e32 v35, v35
	v_add_f32_e32 v132, 1.0, v34
	v_rcp_f32_e32 v131, v131
	v_min_f32_e64 v36, -v36, s60
	v_rcp_f32_e32 v132, v132
	v_exp_f32_e32 v36, v36
	v_add_f32_e32 v133, 1.0, v130
	v_rcp_f32_e32 v136, v133
	v_mul_f32_e32 v32, v32, v35
	v_mul_f32_e32 v133, v135, v35
	v_mul_f32_e32 v33, v33, v131
	v_mul_f32_e32 v137, v135, v131
	v_cndmask_b32_e32 v35, 1.0, v32, vcc
	v_cndmask_b32_e32 v138, 0, v133, vcc
	v_cmp_lt_i32_e32 vcc, 1, v134
	v_mul_f32_e32 v34, v34, v132
	v_mul_f32_e32 v32, v135, v132
	v_cndmask_b32_e32 v131, 1.0, v33, vcc
	v_cndmask_b32_e32 v137, 0, v137, vcc
	v_cmp_lt_i32_e32 vcc, 2, v134
	v_min_f32_e64 v39, -v39, s60
	v_cndmask_b32_e32 v33, 1.0, v34, vcc
	v_add_f32_e32 v34, 1.0, v36
	v_rcp_f32_e32 v34, v34
	v_cndmask_b32_e32 v139, 0, v32, vcc
	v_mul_f32_e32 v32, v130, v136
	v_cmp_lt_i32_e32 vcc, 3, v134
	v_exp_f32_e32 v39, v39
	v_cndmask_b32_e32 v133, 1.0, v32, vcc
	v_mul_f32_e32 v32, v135, v136
	v_cndmask_b32_e32 v136, 0, v32, vcc
	v_mul_f32_e32 v32, v36, v34
	v_min_f32_e64 v36, -v37, s60
	v_exp_f32_e32 v36, v36
	v_cmp_lt_i32_e32 vcc, 8, v134
	v_mul_f32_e32 v34, v135, v34
	v_cndmask_b32_e32 v140, 0, v34, vcc
	v_add_f32_e32 v34, 1.0, v36
	v_rcp_f32_e32 v34, v34
	v_min_f32_e64 v37, -v38, s60
	v_exp_f32_e32 v37, v37
	v_cndmask_b32_e32 v32, 1.0, v32, vcc
	v_mul_f32_e32 v36, v36, v34
	v_cmp_lt_i32_e32 vcc, 9, v134
	v_mul_f32_e32 v34, v135, v34
	v_min_f32_e64 v42, -v42, s60
	v_cndmask_b32_e32 v38, 1.0, v36, vcc
	v_add_f32_e32 v36, 1.0, v37
	v_rcp_f32_e32 v36, v36
	v_cndmask_b32_e32 v141, 0, v34, vcc
	v_cmp_lt_i32_e32 vcc, 10, v134
	v_exp_f32_e32 v42, v42
	v_mul_f32_e32 v34, v37, v36
	v_add_f32_e32 v37, 1.0, v39
	v_rcp_f32_e32 v37, v37
	v_cndmask_b32_e32 v142, 1.0, v34, vcc
	v_mul_f32_e32 v34, v135, v36
	v_cndmask_b32_e32 v143, 0, v34, vcc
	v_mul_f32_e32 v34, v39, v37
	v_cmp_lt_i32_e32 vcc, 11, v134
	v_min_f32_e64 v36, -v40, s60
	v_exp_f32_e32 v36, v36
	v_cndmask_b32_e32 v39, 1.0, v34, vcc
	v_mul_f32_e32 v34, v135, v37
	v_min_f32_e64 v37, -v41, s60
	v_exp_f32_e32 v37, v37
	v_cndmask_b32_e32 v40, 0, v34, vcc
	v_add_f32_e32 v34, 1.0, v36
	v_rcp_f32_e32 v34, v34
	v_add_f32_e32 v41, 1.0, v37
	v_rcp_f32_e32 v41, v41
	v_cmp_lt_i32_e32 vcc, 16, v134
	v_mul_f32_e32 v36, v36, v34
	v_mul_f32_e32 v34, v135, v34
	v_cndmask_b32_e32 v144, 0, v34, vcc
	v_mul_f32_e32 v34, v37, v41
	v_add_f32_e32 v37, 1.0, v42
	v_rcp_f32_e32 v37, v37
	v_cndmask_b32_e32 v36, 1.0, v36, vcc
	v_cmp_lt_i32_e32 vcc, 17, v134
	v_min_f32_e64 v45, -v45, s60
	v_cndmask_b32_e32 v145, 1.0, v34, vcc
	v_mul_f32_e32 v34, v135, v41
	v_cndmask_b32_e32 v41, 0, v34, vcc
	v_mul_f32_e32 v34, v42, v37
	v_cmp_lt_i32_e32 vcc, 18, v134
	v_min_f32_e64 v42, -v43, s60
	v_exp_f32_e32 v42, v42
	v_cndmask_b32_e32 v43, 1.0, v34, vcc
	v_mul_f32_e32 v34, v135, v37
	v_min_f32_e64 v37, -v44, s60
	v_exp_f32_e32 v37, v37
	v_cndmask_b32_e32 v146, 0, v34, vcc
	v_add_f32_e32 v34, 1.0, v42
	v_rcp_f32_e32 v34, v34
	v_add_f32_e32 v44, 1.0, v37
	v_rcp_f32_e32 v44, v44
	v_exp_f32_e32 v45, v45
	v_min_f32_e64 v46, -v46, s60
	v_min_f32_e64 v47, -v47, s60
	v_exp_f32_e32 v46, v46
	v_exp_f32_e32 v47, v47
	v_mul_f32_e32 v42, v42, v34
	v_cmp_lt_i32_e32 vcc, 19, v134
	v_mul_f32_e32 v34, v135, v34
	v_add_f32_e32 v130, 1.0, v46
	v_cndmask_b32_e32 v147, 0, v34, vcc
	v_mul_f32_e32 v34, v37, v44
	v_add_f32_e32 v37, 1.0, v45
	v_rcp_f32_e32 v37, v37
	v_add_f32_e32 v132, 1.0, v47
	v_rcp_f32_e32 v130, v130
	v_rcp_f32_e32 v132, v132
	v_cndmask_b32_e32 v42, 1.0, v42, vcc
	v_cmp_lt_i32_e32 vcc, 24, v134
	v_mul_f32_e32 v44, v135, v44
	v_mul_f32_e32 v45, v45, v37
	v_cndmask_b32_e32 v34, 1.0, v34, vcc
	v_cndmask_b32_e32 v44, 0, v44, vcc
	v_cmp_lt_i32_e32 vcc, 25, v134
	v_mul_f32_e32 v37, v135, v37
	v_mul_f32_e32 v46, v46, v130
	v_cndmask_b32_e32 v45, 1.0, v45, vcc
	v_cndmask_b32_e32 v37, 0, v37, vcc
	v_cmp_lt_i32_e32 vcc, 26, v134
	v_mul_f32_e32 v47, v47, v132
	v_cndmask_b32_e64 v47, 1.0, v47, s[0:1]
	v_cndmask_b32_e32 v46, 1.0, v46, vcc
	v_mul_f32_e32 v34, v34, v45
	v_mul_f32_e32 v134, v46, v47
	v_mul_f32_e32 v134, v34, v134
	v_mov_b32_e32 v148, v134
	v_mov_b32_e32 v240, v134
	s_nop 1
	v_permlane32_swap_b32_e32 v148, v240
	v_cndmask_b32_e64 v148, v148, v240, s[2:3]
	v_mul_f32_e32 v34, v135, v130
	v_cndmask_b32_e32 v149, 0, v34, vcc
	v_mul_f32_e32 v34, v135, v132
	v_cndmask_b32_e64 v34, 0, v34, s[0:1]
	s_waitcnt lgkmcnt(0)
	v_cndmask_b32_e64 v130, 1.0, v148, s[2:3]
	v_mul_f32_e32 v135, v34, v130
	v_mul_f32_e32 v34, v36, v145
	v_mul_f32_e32 v36, v43, v42
	v_mul_f32_e32 v36, v34, v36
	v_mul_f32_e32 v32, v32, v38
	v_mul_f32_e32 v34, v142, v39
	v_mov_b32_e32 v150, v36
	v_mov_b32_e32 v240, v36
	s_nop 1
	v_permlane32_swap_b32_e32 v150, v240
	v_cndmask_b32_e64 v150, v150, v240, s[2:3]
	v_mul_f32_e32 v34, v32, v34
	v_mul_f32_e32 v47, v47, v130
	v_mov_b32_e32 v130, v34
	v_mov_b32_e32 v240, v34
	s_nop 1
	v_permlane32_swap_b32_e32 v130, v240
	v_cndmask_b32_e64 v130, v130, v240, s[2:3]
	v_mul_f32_e32 v46, v46, v47
	v_mul_f32_e32 v32, v134, v148
	s_waitcnt lgkmcnt(1)
	v_mul_f32_e32 v132, v36, v150
	v_mul_f32_e32 v45, v45, v46
	v_mul_f32_e32 v46, v37, v46
	s_waitcnt lgkmcnt(0)
	v_cndmask_b32_e64 v134, 1.0, v130, s[2:3]
	v_pk_mul_f32 v[36:37], v[32:33], v[132:133]
	v_pk_mul_f32 v[34:35], v[34:35], v[130:131]
	v_mul_f32_e32 v132, v36, v134
	v_mul_f32_e32 v134, v39, v132
	v_mul_f32_e32 v142, v142, v134
	v_mul_f32_e32 v148, v38, v142
	v_pk_mul_f32 v[38:39], v[34:35], v[36:37]
	v_mov_b32_e32 v130, v39
	v_mov_b32_e32 v240, v39
	s_nop 1
	v_permlane32_swap_b32_e32 v130, v240
	v_cndmask_b32_e64 v130, v130, v240, s[2:3]
	v_mul_f32_e32 v37, v40, v132
	v_mul_f32_e32 v40, v143, v134
	v_mul_f32_e32 v36, v141, v142
	v_mul_f32_e32 v132, v140, v148
	s_waitcnt lgkmcnt(0)
	v_cndmask_b32_e64 v34, 1.0, v130, s[2:3]
	v_mul_f32_e32 v34, v38, v34
	v_mul_f32_e32 v35, v133, v34
	v_mul_f32_e32 v33, v33, v35
	v_mul_f32_e32 v131, v131, v33
	v_mul_f32_e32 v133, v136, v34
	v_mul_f32_e32 v35, v139, v35
	v_mul_f32_e32 v33, v137, v33
	v_mul_f32_e32 v34, v138, v131
	v_cvt_pk_bf16_f32 v34, v34, v33
	v_cvt_pk_bf16_f32 v35, v35, v133
	v_cvt_pk_bf16_f32 v36, v132, v36
	v_cvt_pk_bf16_f32 v37, v40, v37
	v_cndmask_b32_e64 v33, 1.0, v150, s[2:3]
	v_mul_f32_e32 v32, v32, v33
	v_mfma_f32_32x32x16_bf16 v[0:15], v[92:95], v[34:37], v[0:15]
	v_mul_f32_e32 v33, v42, v32
	v_mul_f32_e32 v42, v43, v33
	v_mul_f32_e32 v43, v145, v42
	v_mul_f32_e32 v47, v149, v47
	v_mul_f32_e32 v40, v44, v45
	v_mul_f32_e32 v44, v147, v32
	v_mul_f32_e32 v33, v146, v33
	v_mfma_f32_32x32x16_bf16 v[16:31], v[88:91], v[34:37], v[16:31]
	v_mul_f32_e32 v32, v41, v42
	v_mul_f32_e32 v34, v144, v43
	v_cvt_pk_bf16_f32 v32, v34, v32
	v_cvt_pk_bf16_f32 v33, v33, v44
	v_cvt_pk_bf16_f32 v34, v40, v46
	v_cvt_pk_bf16_f32 v35, v47, v135
	v_mul_f32_e32 v36, v39, v130
	v_mul_f32_e32 v36, v38, v36
	v_mfma_f32_32x32x16_bf16 v[0:15], v[84:87], v[32:35], v[0:15]
	v_log_f32_e32 v36, v36
	s_nop 0
	v_add_f32_e32 v126, v126, v36
	v_mfma_f32_32x32x16_bf16 v[16:31], v[80:83], v[32:35], v[16:31]
; __device__ __forceinline__ void sb_unit(const Frame& F, int b, int hd, int qi, int dry) {
;     ...
;             float run = C;
;             if (!meta && key0 + 96 < tqw + 31) SB_HALF(96);
;             if (!meta && key0 + 64 < tqw + 31 && __any(run >= SB_DEAD)) SB_HALF(64);
;             if (!meta && key0 + 32 < tqw + 31 && __any(run >= SB_DEAD)) SB_HALF(32);
.LBB0_367:
	s_or_b32 s0, s34, 1
	s_cmp_ge_i32 s0, s25
	s_cselect_b64 s[0:1], -1, 0
	s_or_b64 s[0:1], s[18:19], s[0:1]
	s_and_b64 vcc, exec, s[0:1]
	s_cbranch_vccnz .LBB0_370
	v_cmp_le_f32_e32 vcc, s22, v126
	s_cbranch_vccz .LBB0_370
	ds_read_b128 v[32:35], v129 offset:4608
	ds_read_b128 v[214:217], v129 offset:4640
	ds_read_b128 v[210:213], v129 offset:4672
	ds_read_b128 v[130:133], v129 offset:4704
	ds_read_b64_tr_b16 v[92:93], v128 offset:43008
	ds_read_b64_tr_b16 v[94:95], v128 offset:44544
	ds_read_b64_tr_b16 v[90:91], v128 offset:44608
	ds_read_b64_tr_b16 v[88:89], v128 offset:43072
	ds_read_b64_tr_b16 v[84:85], v128 offset:46080
	ds_read_b64_tr_b16 v[86:87], v128 offset:47616
	ds_read_b64_tr_b16 v[82:83], v128 offset:47680
	ds_read_b64_tr_b16 v[80:81], v128 offset:46144
	v_exp_f32_e32 v135, v126
	v_sub_u32_e32 v134, v125, v127
	v_cmp_lt_i32_e32 vcc, 0, v134
	s_waitcnt lgkmcnt(11)
	v_mfma_f32_32x32x16_bf16 v[32:47], v[32:35], v[48:51], 0
	v_cmp_lt_i32_e64 s[0:1], 27, v134
	s_waitcnt lgkmcnt(10)
	v_mfma_f32_32x32x16_bf16 v[32:47], v[214:217], v[52:55], v[32:47]
	s_waitcnt lgkmcnt(9)
	v_mfma_f32_32x32x16_bf16 v[32:47], v[210:213], v[56:59], v[32:47]
	s_waitcnt lgkmcnt(8)
	v_mfma_f32_32x32x16_bf16 v[32:47], v[130:133], v[60:63], v[32:47]
	s_nop 11
	v_min_f32_e64 v32, -v32, s60
	v_min_f32_e64 v33, -v33, s60
	v_exp_f32_e32 v32, v32
	v_min_f32_e64 v34, -v34, s60
	v_exp_f32_e32 v33, v33
	v_exp_f32_e32 v34, v34
	v_min_f32_e64 v35, -v35, s60
	v_exp_f32_e32 v130, v35
	v_add_f32_e32 v35, 1.0, v32
	v_add_f32_e32 v131, 1.0, v33
	v_rcp_f32_e32 v35, v35
	v_add_f32_e32 v132, 1.0, v34
	v_rcp_f32_e32 v131, v131
	v_min_f32_e64 v36, -v36, s60
	v_rcp_f32_e32 v132, v132
	v_exp_f32_e32 v36, v36
	v_add_f32_e32 v133, 1.0, v130
	v_rcp_f32_e32 v136, v133
	v_mul_f32_e32 v32, v32, v35
	v_mul_f32_e32 v133, v135, v35
	v_mul_f32_e32 v33, v33, v131
	v_mul_f32_e32 v137, v135, v131
	v_cndmask_b32_e32 v35, 1.0, v32, vcc
	v_cndmask_b32_e32 v138, 0, v133, vcc
	v_cmp_lt_i32_e32 vcc, 1, v134
	v_mul_f32_e32 v34, v34, v132
	v_mul_f32_e32 v32, v135, v132
	v_cndmask_b32_e32 v131, 1.0, v33, vcc
	v_cndmask_b32_e32 v137, 0, v137, vcc
	v_cmp_lt_i32_e32 vcc, 2, v134
	v_min_f32_e64 v39, -v39, s60
	v_cndmask_b32_e32 v33, 1.0, v34, vcc
	v_add_f32_e32 v34, 1.0, v36
	v_rcp_f32_e32 v34, v34
	v_cndmask_b32_e32 v139, 0, v32, vcc
	v_mul_f32_e32 v32, v130, v136
	v_cmp_lt_i32_e32 vcc, 3, v134
	v_exp_f32_e32 v39, v39
	v_cndmask_b32_e32 v133, 1.0, v32, vcc
	v_mul_f32_e32 v32, v135, v136
	v_cndmask_b32_e32 v136, 0, v32, vcc
	v_mul_f32_e32 v32, v36, v34
	v_min_f32_e64 v36, -v37, s60
	v_exp_f32_e32 v36, v36
	v_cmp_lt_i32_e32 vcc, 8, v134
	v_mul_f32_e32 v34, v135, v34
	v_cndmask_b32_e32 v140, 0, v34, vcc
	v_add_f32_e32 v34, 1.0, v36
	v_rcp_f32_e32 v34, v34
	v_min_f32_e64 v37, -v38, s60
	v_exp_f32_e32 v37, v37
	v_cndmask_b32_e32 v32, 1.0, v32, vcc
	v_mul_f32_e32 v36, v36, v34
	v_cmp_lt_i32_e32 vcc, 9, v134
	v_mul_f32_e32 v34, v135, v34
	v_min_f32_e64 v42, -v42, s60
	v_cndmask_b32_e32 v38, 1.0, v36, vcc
	v_add_f32_e32 v36, 1.0, v37
	v_rcp_f32_e32 v36, v36
	v_cndmask_b32_e32 v141, 0, v34, vcc
	v_cmp_lt_i32_e32 vcc, 10, v134
	v_exp_f32_e32 v42, v42
	v_mul_f32_e32 v34, v37, v36
	v_add_f32_e32 v37, 1.0, v39
	v_rcp_f32_e32 v37, v37
	v_cndmask_b32_e32 v142, 1.0, v34, vcc
	v_mul_f32_e32 v34, v135, v36
	v_cndmask_b32_e32 v143, 0, v34, vcc
	v_mul_f32_e32 v34, v39, v37
	v_cmp_lt_i32_e32 vcc, 11, v134
	v_min_f32_e64 v36, -v40, s60
	v_exp_f32_e32 v36, v36
	v_cndmask_b32_e32 v39, 1.0, v34, vcc
	v_mul_f32_e32 v34, v135, v37
	v_min_f32_e64 v37, -v41, s60
	v_exp_f32_e32 v37, v37
	v_cndmask_b32_e32 v40, 0, v34, vcc
	v_add_f32_e32 v34, 1.0, v36
	v_rcp_f32_e32 v34, v34
	v_add_f32_e32 v41, 1.0, v37
	v_rcp_f32_e32 v41, v41
	v_cmp_lt_i32_e32 vcc, 16, v134
	v_mul_f32_e32 v36, v36, v34
	v_mul_f32_e32 v34, v135, v34
	v_cndmask_b32_e32 v144, 0, v34, vcc
	v_mul_f32_e32 v34, v37, v41
	v_add_f32_e32 v37, 1.0, v42
	v_rcp_f32_e32 v37, v37
	v_cndmask_b32_e32 v36, 1.0, v36, vcc
	v_cmp_lt_i32_e32 vcc, 17, v134
	v_min_f32_e64 v45, -v45, s60
	v_cndmask_b32_e32 v145, 1.0, v34, vcc
	v_mul_f32_e32 v34, v135, v41
	v_cndmask_b32_e32 v41, 0, v34, vcc
	v_mul_f32_e32 v34, v42, v37
	v_cmp_lt_i32_e32 vcc, 18, v134
	v_min_f32_e64 v42, -v43, s60
	v_exp_f32_e32 v42, v42
	v_cndmask_b32_e32 v43, 1.0, v34, vcc
	v_mul_f32_e32 v34, v135, v37
	v_min_f32_e64 v37, -v44, s60
	v_exp_f32_e32 v37, v37
	v_cndmask_b32_e32 v146, 0, v34, vcc
	v_add_f32_e32 v34, 1.0, v42
	v_rcp_f32_e32 v34, v34
	v_add_f32_e32 v44, 1.0, v37
	v_rcp_f32_e32 v44, v44
	v_exp_f32_e32 v45, v45
	v_min_f32_e64 v46, -v46, s60
	v_min_f32_e64 v47, -v47, s60
	v_exp_f32_e32 v46, v46
	v_exp_f32_e32 v47, v47
	v_mul_f32_e32 v42, v42, v34
	v_cmp_lt_i32_e32 vcc, 19, v134
	v_mul_f32_e32 v34, v135, v34
	v_add_f32_e32 v130, 1.0, v46
	v_cndmask_b32_e32 v147, 0, v34, vcc
	v_mul_f32_e32 v34, v37, v44
	v_add_f32_e32 v37, 1.0, v45
	v_rcp_f32_e32 v37, v37
	v_add_f32_e32 v132, 1.0, v47
	v_rcp_f32_e32 v130, v130
	v_rcp_f32_e32 v132, v132
	v_cndmask_b32_e32 v42, 1.0, v42, vcc
	v_cmp_lt_i32_e32 vcc, 24, v134
	v_mul_f32_e32 v44, v135, v44
	v_mul_f32_e32 v45, v45, v37
	v_cndmask_b32_e32 v34, 1.0, v34, vcc
	v_cndmask_b32_e32 v44, 0, v44, vcc
	v_cmp_lt_i32_e32 vcc, 25, v134
	v_mul_f32_e32 v37, v135, v37
	v_mul_f32_e32 v46, v46, v130
	v_cndmask_b32_e32 v45, 1.0, v45, vcc
	v_cndmask_b32_e32 v37, 0, v37, vcc
	v_cmp_lt_i32_e32 vcc, 26, v134
	v_mul_f32_e32 v47, v47, v132
	v_cndmask_b32_e64 v47, 1.0, v47, s[0:1]
	v_cndmask_b32_e32 v46, 1.0, v46, vcc
	v_mul_f32_e32 v34, v34, v45
	v_mul_f32_e32 v134, v46, v47
	v_mul_f32_e32 v134, v34, v134
	v_mov_b32_e32 v148, v134
	v_mov_b32_e32 v240, v134
	s_nop 1
	v_permlane32_swap_b32_e32 v148, v240
	v_cndmask_b32_e64 v148, v148, v240, s[2:3]
	v_mul_f32_e32 v34, v135, v130
	v_cndmask_b32_e32 v149, 0, v34, vcc
	v_mul_f32_e32 v34, v135, v132
	v_cndmask_b32_e64 v34, 0, v34, s[0:1]
	s_waitcnt lgkmcnt(0)
; __device__ __forceinline__ void sb_unit(const Frame& F, int b, int hd, int qi, int dry) {
;     ...
;             float run = C;
;             if (!meta && key0 + 96 < tqw + 31) SB_HALF(96);
;             if (!meta && key0 + 64 < tqw + 31 && __any(run >= SB_DEAD)) SB_HALF(64);
;             if (!meta && key0 + 32 < tqw + 31 && __any(run >= SB_DEAD)) SB_HALF(32);
;             if (__any(run >= SB_DEAD)) SB_HALF(0);
	v_cndmask_b32_e64 v130, 1.0, v148, s[2:3]
	v_mul_f32_e32 v135, v34, v130
	v_mul_f32_e32 v34, v36, v145
	v_mul_f32_e32 v36, v43, v42
	v_mul_f32_e32 v36, v34, v36
	v_mul_f32_e32 v32, v32, v38
	v_mul_f32_e32 v34, v142, v39
	v_mov_b32_e32 v150, v36
	v_mov_b32_e32 v240, v36
	s_nop 1
	v_permlane32_swap_b32_e32 v150, v240
	v_cndmask_b32_e64 v150, v150, v240, s[2:3]
	v_mul_f32_e32 v34, v32, v34
	v_mul_f32_e32 v47, v47, v130
	v_mov_b32_e32 v130, v34
	v_mov_b32_e32 v240, v34
	s_nop 1
	v_permlane32_swap_b32_e32 v130, v240
	v_cndmask_b32_e64 v130, v130, v240, s[2:3]
	v_mul_f32_e32 v46, v46, v47
	v_mul_f32_e32 v32, v134, v148
	s_waitcnt lgkmcnt(1)
	v_mul_f32_e32 v132, v36, v150
	v_mul_f32_e32 v45, v45, v46
	v_mul_f32_e32 v46, v37, v46
	s_waitcnt lgkmcnt(0)
	v_cndmask_b32_e64 v134, 1.0, v130, s[2:3]
	v_pk_mul_f32 v[36:37], v[32:33], v[132:133]
	v_pk_mul_f32 v[34:35], v[34:35], v[130:131]
	v_mul_f32_e32 v132, v36, v134
	v_mul_f32_e32 v134, v39, v132
	v_mul_f32_e32 v142, v142, v134
	v_mul_f32_e32 v148, v38, v142
	v_pk_mul_f32 v[38:39], v[34:35], v[36:37]
	v_mov_b32_e32 v130, v39
	v_mov_b32_e32 v240, v39
	s_nop 1
	v_permlane32_swap_b32_e32 v130, v240
	v_cndmask_b32_e64 v130, v130, v240, s[2:3]
	v_mul_f32_e32 v37, v40, v132
	v_mul_f32_e32 v40, v143, v134
	v_mul_f32_e32 v36, v141, v142
	v_mul_f32_e32 v132, v140, v148
	s_waitcnt lgkmcnt(0)
	v_cndmask_b32_e64 v34, 1.0, v130, s[2:3]
	v_mul_f32_e32 v34, v38, v34
	v_mul_f32_e32 v35, v133, v34
	v_mul_f32_e32 v33, v33, v35
	v_mul_f32_e32 v131, v131, v33
	v_mul_f32_e32 v133, v136, v34
	v_mul_f32_e32 v35, v139, v35
	v_mul_f32_e32 v33, v137, v33
	v_mul_f32_e32 v34, v138, v131
	v_cvt_pk_bf16_f32 v34, v34, v33
	v_cvt_pk_bf16_f32 v35, v35, v133
	v_cvt_pk_bf16_f32 v36, v132, v36
	v_cvt_pk_bf16_f32 v37, v40, v37
	v_cndmask_b32_e64 v33, 1.0, v150, s[2:3]
	v_mul_f32_e32 v32, v32, v33
	v_mfma_f32_32x32x16_bf16 v[0:15], v[92:95], v[34:37], v[0:15]
	v_mul_f32_e32 v33, v42, v32
	v_mul_f32_e32 v42, v43, v33
	v_mul_f32_e32 v43, v145, v42
	v_mul_f32_e32 v47, v149, v47
	v_mul_f32_e32 v40, v44, v45
	v_mul_f32_e32 v44, v147, v32
	v_mul_f32_e32 v33, v146, v33
	v_mfma_f32_32x32x16_bf16 v[16:31], v[88:91], v[34:37], v[16:31]
	v_mul_f32_e32 v32, v41, v42
	v_mul_f32_e32 v34, v144, v43
	v_cvt_pk_bf16_f32 v32, v34, v32
	v_cvt_pk_bf16_f32 v33, v33, v44
	v_cvt_pk_bf16_f32 v34, v40, v46
	v_cvt_pk_bf16_f32 v35, v47, v135
	v_mul_f32_e32 v36, v39, v130
	v_mul_f32_e32 v36, v38, v36
	v_mfma_f32_32x32x16_bf16 v[0:15], v[84:87], v[32:35], v[0:15]
	v_log_f32_e32 v36, v36
	s_nop 0
	v_add_f32_e32 v126, v126, v36
	v_mfma_f32_32x32x16_bf16 v[16:31], v[80:83], v[32:35], v[16:31]
.LBB0_370:
	v_cmp_le_f32_e32 vcc, s22, v126
	s_cbranch_vccz .LBB0_372
	ds_read_b128 v[32:35], v129
	ds_read_b128 v[214:217], v129 offset:32
	ds_read_b128 v[210:213], v129 offset:64
	ds_read_b128 v[130:133], v129 offset:96
	ds_read_b64_tr_b16 v[92:93], v128 offset:36864
	ds_read_b64_tr_b16 v[94:95], v128 offset:38400
	ds_read_b64_tr_b16 v[90:91], v128 offset:38464
	ds_read_b64_tr_b16 v[88:89], v128 offset:36928
	ds_read_b64_tr_b16 v[84:85], v128 offset:39936
	ds_read_b64_tr_b16 v[86:87], v128 offset:41472
	ds_read_b64_tr_b16 v[82:83], v128 offset:41536
	ds_read_b64_tr_b16 v[80:81], v128 offset:40000
	v_cndmask_b32_e64 v129, v114, 16, s[18:19]
	v_sub_u32_e32 v127, v129, v127
	v_cmp_lt_i32_e32 vcc, 0, v127
	v_cmp_lt_i32_e64 s[0:1], 27, v127
	v_exp_f32_e32 v128, v126
	s_waitcnt lgkmcnt(11)
	v_mfma_f32_32x32x16_bf16 v[32:47], v[32:35], v[48:51], 0
	s_waitcnt lgkmcnt(10)
	v_mfma_f32_32x32x16_bf16 v[32:47], v[214:217], v[52:55], v[32:47]
	s_waitcnt lgkmcnt(9)
	v_mfma_f32_32x32x16_bf16 v[32:47], v[210:213], v[56:59], v[32:47]
	s_waitcnt lgkmcnt(8)
	v_mfma_f32_32x32x16_bf16 v[32:47], v[130:133], v[60:63], v[32:47]
	s_nop 11
	v_min_f32_e64 v32, -v32, s60
	v_min_f32_e64 v33, -v33, s60
	v_exp_f32_e32 v32, v32
	v_min_f32_e64 v34, -v34, s60
	v_exp_f32_e32 v33, v33
	v_exp_f32_e32 v34, v34
	v_min_f32_e64 v35, -v35, s60
	v_exp_f32_e32 v130, v35
	v_add_f32_e32 v35, 1.0, v32
	v_add_f32_e32 v129, 1.0, v33
	v_rcp_f32_e32 v35, v35
	v_add_f32_e32 v131, 1.0, v34
	v_rcp_f32_e32 v129, v129
	v_rcp_f32_e32 v131, v131
	v_add_f32_e32 v132, 1.0, v130
	v_rcp_f32_e32 v132, v132
	v_mul_f32_e32 v32, v32, v35
	v_mul_f32_e32 v133, v128, v35
	v_min_f32_e64 v36, -v36, s60
	v_mul_f32_e32 v33, v33, v129
	v_mul_f32_e32 v134, v128, v129
	v_cndmask_b32_e32 v35, 1.0, v32, vcc
	v_cndmask_b32_e32 v133, 0, v133, vcc
	v_cmp_lt_i32_e32 vcc, 1, v127
	v_mul_f32_e32 v34, v34, v131
	v_exp_f32_e32 v32, v36
	v_cndmask_b32_e32 v129, 1.0, v33, vcc
	v_cndmask_b32_e32 v134, 0, v134, vcc
	v_cmp_lt_i32_e32 vcc, 2, v127
	v_add_f32_e32 v36, 1.0, v32
	v_rcp_f32_e32 v36, v36
	v_cndmask_b32_e32 v33, 1.0, v34, vcc
	v_mul_f32_e32 v34, v128, v131
	v_cndmask_b32_e32 v135, 0, v34, vcc
	v_mul_f32_e32 v34, v130, v132
	v_cmp_lt_i32_e32 vcc, 3, v127
	v_mul_f32_e32 v32, v32, v36
	v_mul_f32_e32 v36, v128, v36
	v_cndmask_b32_e32 v131, 1.0, v34, vcc
	v_mul_f32_e32 v34, v128, v132
	v_cndmask_b32_e32 v132, 0, v34, vcc
	v_min_f32_e64 v34, -v37, s60
	v_exp_f32_e32 v34, v34
	v_cmp_lt_i32_e32 vcc, 8, v127
	v_min_f32_e64 v37, -v38, s60
	v_cndmask_b32_e32 v136, 0, v36, vcc
	v_add_f32_e32 v36, 1.0, v34
	v_rcp_f32_e32 v36, v36
	v_exp_f32_e32 v37, v37
	v_cndmask_b32_e32 v32, 1.0, v32, vcc
	v_cmp_lt_i32_e32 vcc, 9, v127
	v_mul_f32_e32 v34, v34, v36
	v_cndmask_b32_e32 v38, 1.0, v34, vcc
	v_add_f32_e32 v34, 1.0, v37
	v_min_f32_e64 v39, -v39, s60
	v_rcp_f32_e32 v34, v34
	v_exp_f32_e32 v39, v39
	v_mul_f32_e32 v36, v128, v36
	v_cndmask_b32_e32 v137, 0, v36, vcc
	v_mul_f32_e32 v36, v37, v34
	v_add_f32_e32 v37, 1.0, v39
	v_rcp_f32_e32 v37, v37
	v_cmp_lt_i32_e32 vcc, 10, v127
	v_mul_f32_e32 v34, v128, v34
	v_cndmask_b32_e32 v138, 1.0, v36, vcc
	v_cndmask_b32_e32 v139, 0, v34, vcc
	v_mul_f32_e32 v34, v39, v37
	v_cmp_lt_i32_e32 vcc, 11, v127
	v_min_f32_e64 v36, -v40, s60
	v_exp_f32_e32 v36, v36
	v_cndmask_b32_e32 v39, 1.0, v34, vcc
	v_mul_f32_e32 v34, v128, v37
	v_min_f32_e64 v37, -v41, s60
	v_exp_f32_e32 v37, v37
	v_cndmask_b32_e32 v40, 0, v34, vcc
	v_add_f32_e32 v34, 1.0, v36
	v_rcp_f32_e32 v34, v34
	v_add_f32_e32 v41, 1.0, v37
	v_min_f32_e64 v42, -v42, s60
	v_rcp_f32_e32 v41, v41
	v_exp_f32_e32 v42, v42
	v_mul_f32_e32 v36, v36, v34
	v_cmp_lt_i32_e32 vcc, 16, v127
	v_mul_f32_e32 v34, v128, v34
	v_cndmask_b32_e32 v140, 0, v34, vcc
	v_mul_f32_e32 v34, v37, v41
	v_add_f32_e32 v37, 1.0, v42
	v_rcp_f32_e32 v37, v37
	v_cndmask_b32_e32 v36, 1.0, v36, vcc
	v_cmp_lt_i32_e32 vcc, 17, v127
	v_min_f32_e64 v45, -v45, s60
	v_cndmask_b32_e32 v141, 1.0, v34, vcc
	v_mul_f32_e32 v34, v128, v41
	v_cndmask_b32_e32 v41, 0, v34, vcc
	v_mul_f32_e32 v34, v42, v37
	v_cmp_lt_i32_e32 vcc, 18, v127
	v_min_f32_e64 v42, -v43, s60
	v_exp_f32_e32 v42, v42
	v_cndmask_b32_e32 v43, 1.0, v34, vcc
	v_mul_f32_e32 v34, v128, v37
	v_min_f32_e64 v37, -v44, s60
	v_exp_f32_e32 v37, v37
	v_cndmask_b32_e32 v142, 0, v34, vcc
	v_add_f32_e32 v34, 1.0, v42
	v_rcp_f32_e32 v34, v34
	v_add_f32_e32 v44, 1.0, v37
	v_rcp_f32_e32 v44, v44
	v_exp_f32_e32 v45, v45
	v_min_f32_e64 v46, -v46, s60
	v_min_f32_e64 v47, -v47, s60
	v_exp_f32_e32 v46, v46
	v_exp_f32_e32 v47, v47
	v_mul_f32_e32 v42, v42, v34
	v_cmp_lt_i32_e32 vcc, 19, v127
	v_mul_f32_e32 v34, v128, v34
	v_add_f32_e32 v130, 1.0, v46
	v_cndmask_b32_e32 v143, 0, v34, vcc
	v_mul_f32_e32 v34, v37, v44
	v_add_f32_e32 v37, 1.0, v45
	v_rcp_f32_e32 v37, v37
	v_add_f32_e32 v144, 1.0, v47
	v_rcp_f32_e32 v130, v130
	v_rcp_f32_e32 v144, v144
	v_cndmask_b32_e32 v42, 1.0, v42, vcc
	v_cmp_lt_i32_e32 vcc, 24, v127
	v_mul_f32_e32 v44, v128, v44
	v_mul_f32_e32 v45, v45, v37
	v_cndmask_b32_e32 v34, 1.0, v34, vcc
	v_cndmask_b32_e32 v44, 0, v44, vcc
	v_cmp_lt_i32_e32 vcc, 25, v127
	v_mul_f32_e32 v37, v128, v37
	v_mul_f32_e32 v46, v46, v130
	v_cndmask_b32_e32 v45, 1.0, v45, vcc
	v_cndmask_b32_e32 v37, 0, v37, vcc
	v_cmp_lt_i32_e32 vcc, 26, v127
	v_mul_f32_e32 v47, v47, v144
	v_cndmask_b32_e64 v47, 1.0, v47, s[0:1]
	v_cndmask_b32_e32 v46, 1.0, v46, vcc
	v_mul_f32_e32 v34, v34, v45
	v_mul_f32_e32 v127, v46, v47
	v_mul_f32_e32 v127, v34, v127
	v_mov_b32_e32 v145, v127
	v_mov_b32_e32 v240, v127
	s_nop 1
	v_permlane32_swap_b32_e32 v145, v240
	v_cndmask_b32_e64 v145, v145, v240, s[2:3]
	v_mul_f32_e32 v34, v128, v130
	v_cndmask_b32_e32 v130, 0, v34, vcc
	v_mul_f32_e32 v34, v128, v144
	v_cndmask_b32_e64 v34, 0, v34, s[0:1]
	s_waitcnt lgkmcnt(0)
	v_cndmask_b32_e64 v128, 1.0, v145, s[2:3]
	v_mul_f32_e32 v144, v34, v128
	v_mul_f32_e32 v34, v36, v141
	v_mul_f32_e32 v36, v43, v42
	v_mul_f32_e32 v36, v34, v36
	v_mul_f32_e32 v32, v32, v38
	v_mul_f32_e32 v34, v138, v39
	v_mov_b32_e32 v146, v36
	v_mov_b32_e32 v240, v36
	s_nop 1
	v_permlane32_swap_b32_e32 v146, v240
	v_cndmask_b32_e64 v146, v146, v240, s[2:3]
	v_mul_f32_e32 v34, v32, v34
	v_mul_f32_e32 v47, v47, v128
	v_mov_b32_e32 v128, v34
	v_mov_b32_e32 v240, v34
	s_nop 1
	v_permlane32_swap_b32_e32 v128, v240
	v_cndmask_b32_e64 v128, v128, v240, s[2:3]
	v_mul_f32_e32 v46, v46, v47
	v_mul_f32_e32 v47, v130, v47
	v_mul_f32_e32 v32, v127, v145
	s_waitcnt lgkmcnt(1)
	v_mul_f32_e32 v130, v36, v146
	v_mul_f32_e32 v45, v45, v46
	v_mul_f32_e32 v46, v37, v46
	s_waitcnt lgkmcnt(0)
	v_cndmask_b32_e64 v127, 1.0, v128, s[2:3]
	v_pk_mul_f32 v[36:37], v[32:33], v[130:131]
	v_pk_mul_f32 v[34:35], v[34:35], v[128:129]
	v_mul_f32_e32 v127, v36, v127
	v_mul_f32_e32 v130, v39, v127
	v_mul_f32_e32 v138, v138, v130
	v_mul_f32_e32 v145, v38, v138
	v_pk_mul_f32 v[38:39], v[34:35], v[36:37]
	v_mov_b32_e32 v128, v39
	v_mov_b32_e32 v240, v39
	s_nop 1
	v_permlane32_swap_b32_e32 v128, v240
	v_cndmask_b32_e64 v128, v128, v240, s[2:3]
	v_mul_f32_e32 v37, v40, v127
	v_mul_f32_e32 v40, v139, v130
	v_mul_f32_e32 v36, v137, v138
	v_mul_f32_e32 v127, v136, v145
	s_waitcnt lgkmcnt(0)
	v_cndmask_b32_e64 v34, 1.0, v128, s[2:3]
	v_mul_f32_e32 v34, v38, v34
	v_mul_f32_e32 v35, v131, v34
	v_mul_f32_e32 v33, v33, v35
	v_mul_f32_e32 v129, v129, v33
	v_mul_f32_e32 v130, v132, v34
	v_mul_f32_e32 v35, v135, v35
	v_mul_f32_e32 v33, v134, v33
	v_mul_f32_e32 v34, v133, v129
	v_cvt_pk_bf16_f32 v34, v34, v33
	v_cvt_pk_bf16_f32 v35, v35, v130
	v_cvt_pk_bf16_f32 v36, v127, v36
	v_cvt_pk_bf16_f32 v37, v40, v37
	v_cndmask_b32_e64 v33, 1.0, v146, s[2:3]
	v_mul_f32_e32 v32, v32, v33
	v_mfma_f32_32x32x16_bf16 v[0:15], v[92:95], v[34:37], v[0:15]
	v_mul_f32_e32 v33, v42, v32
	v_mul_f32_e32 v42, v43, v33
	v_mul_f32_e32 v43, v141, v42
	v_mul_f32_e32 v40, v44, v45
	v_mul_f32_e32 v44, v143, v32
	v_mul_f32_e32 v33, v142, v33
	v_mul_f32_e32 v32, v41, v42
	v_mfma_f32_32x32x16_bf16 v[16:31], v[88:91], v[34:37], v[16:31]
	v_mul_f32_e32 v34, v140, v43
	v_cvt_pk_bf16_f32 v32, v34, v32
	v_cvt_pk_bf16_f32 v33, v33, v44
	v_cvt_pk_bf16_f32 v34, v40, v46
	v_cvt_pk_bf16_f32 v35, v47, v144
	v_mul_f32_e32 v36, v39, v128
	v_mul_f32_e32 v36, v38, v36
	v_mfma_f32_32x32x16_bf16 v[0:15], v[84:87], v[32:35], v[0:15]
	v_log_f32_e32 v36, v36
	s_nop 0
	v_add_f32_e32 v126, v126, v36
	v_mfma_f32_32x32x16_bf16 v[16:31], v[80:83], v[32:35], v[16:31]
